# P8 row pass rewritten: 8 rows requested up front, byte-packed quantisation (half the vector instructions)
# baseline (speedup 1.0000x reference)
; __device__ __forceinline__ void xn2_rows(const bf16* __restrict__ hb, const float* __restrict__ g, bf16* __restrict__ outp, unsigned char* __restrict__ xq, float* __restrict__ xs, int gwave, int nwaves, int lane, int rend) {
;     const __amdgpu_buffer_rsrc_t rsO = __builtin_amdgcn_make_buffer_rsrc((void*)outp, 0, (unsigned)T * D * 2u, 0x00020000), rsQ = __builtin_amdgcn_make_buffer_rsrc((void*)xq, 0, 16u * (unsigned)MiB, 0x00020000);
; #pragma unroll 2
;     for (int row = gwave; row < rend; row += nwaves) {
;         const v4u* xb = (const v4u*)(hb + (size_t)row * D) + lane;
;         float v[2][8]; float ss = 0.f;
; #pragma unroll
;         for (int j = 0; j < 2; ++j) { const v4u w = xb[64 * j]; const unsigned ww[4] = {w.x, w.y, w.z, w.w};
; #pragma unroll
;             for (int e = 0; e < 4; ++e) { v[j][2 * e] = __uint_as_float(ww[e] << 16); v[j][2 * e + 1] = __uint_as_float(ww[e] & 0xffff0000u); ss += v[j][2 * e] * v[j][2 * e] + v[j][2 * e + 1] * v[j][2 * e + 1]; } }
;         ss = wave_sum(ss);
;         const float r = rsqrtf(ss * (1.f / D) + EPS);
;         float y[2][8]; float mx = 0.f;
; #pragma unroll
;         for (int j = 0; j < 2; ++j) { const float4 g0 = ((const float4*)g)[2 * lane + 128 * j], g1 = ((const float4*)g)[2 * lane + 128 * j + 1]; const float gg[8] = {g0.x, g0.y, g0.z, g0.w, g1.x, g1.y, g1.z, g1.w};
; #pragma unroll
;             for (int e = 0; e < 8; ++e) { y[j][e] = v[j][e] * r * gg[e]; mx = fmaxf(mx, fabsf(y[j][e])); }
;             v4u ow; ow.x = pk2(y[j][0], y[j][1]); ow.y = pk2(y[j][2], y[j][3]); ow.z = pk2(y[j][4], y[j][5]); ow.w = pk2(y[j][6], y[j][7]);
;             __builtin_amdgcn_raw_buffer_store_b128(ow, rsO, (int)(((unsigned)row * D + 8u * (unsigned)lane + 512u * j) * 2u), 0, 16); }
;         mx = wave_max_dpp(mx);
.LBB0_564:
	s_or_b64 exec, exec, s[10:11]
	s_andn2_b64 vcc, exec, s[20:21]
	s_barrier
	s_cbranch_vccnz .LBB0_569
	global_load_dwordx4 v[2:5], v[20:21], off offset:16
	global_load_dwordx4 v[6:9], v[20:21], off
	global_load_dwordx4 v[10:13], v[20:21], off offset:2064
	global_load_dwordx4 v[14:17], v[20:21], off offset:2048
	s_lshl_b32 s10, s42, 6
	s_lshl_b32 s11, s43, 8
	s_add_i32 s24, s10, s11
	s_add_i32 s24, s24, s95
	s_ashr_i32 s25, s24, 31
	s_lshl_b64 s[10:11], s[24:25], 2
	s_add_u32 s98, s90, s10
	s_addc_u32 s99, s91, s11
	v_lshl_add_u32 v33, s24, 9, v1
	s_lshl_b64 s[24:25], s[24:25], 11
	v_mov_b32_e32 v27, s25
	v_or_b32_e32 v26, s24, v18
	v_lshl_add_u64 v[148:149], s[90:91], 0, v[26:27]
	s_mov_b32 s24, 0xa400000
	s_mov_b32 s25, 0
	s_nop 0
	v_lshl_add_u64 v[148:149], v[148:149], 0, s[24:25]
	global_load_dwordx4 v[84:87], v[148:149], off
	global_load_dwordx4 v[88:91], v[148:149], off offset:1024
	v_lshl_add_u64 v[150:151], v[148:149], 0, s[22:23]
	global_load_dwordx4 v[92:95], v[150:151], off
	global_load_dwordx4 v[96:99], v[150:151], off offset:1024
	v_lshl_add_u64 v[152:153], v[150:151], 0, s[22:23]
	global_load_dwordx4 v[100:103], v[152:153], off
	global_load_dwordx4 v[104:107], v[152:153], off offset:1024
	v_lshl_add_u64 v[154:155], v[152:153], 0, s[22:23]
	global_load_dwordx4 v[108:111], v[154:155], off
	global_load_dwordx4 v[112:115], v[154:155], off offset:1024
	v_lshl_add_u64 v[156:157], v[154:155], 0, s[22:23]
	global_load_dwordx4 v[116:119], v[156:157], off
	global_load_dwordx4 v[120:123], v[156:157], off offset:1024
	v_lshl_add_u64 v[158:159], v[156:157], 0, s[22:23]
	global_load_dwordx4 v[124:127], v[158:159], off
	global_load_dwordx4 v[128:131], v[158:159], off offset:1024
	v_lshl_add_u64 v[160:161], v[158:159], 0, s[22:23]
	global_load_dwordx4 v[132:135], v[160:161], off
	global_load_dwordx4 v[136:139], v[160:161], off offset:1024
	v_lshl_add_u64 v[162:163], v[160:161], 0, s[22:23]
	global_load_dwordx4 v[140:143], v[162:163], off
	global_load_dwordx4 v[144:147], v[162:163], off offset:1024
	s_mov_b32 s46, 0x4b400008
	s_mov_b32 s47, 0x4b400008
	s_mov_b32 s48, 0x0c0c0400
	s_mov_b32 s49, 0x05040100
	s_mov_b32 s45, 0x0f0f0f0f
	v_mov_b32_e32 v55, 0
	v_mov_b32_e32 v61, 0
	s_waitcnt vmcnt(14)
	v_lshlrev_b32_e32 v34, 16, v84
	v_and_b32_e32 v35, 0xffff0000, v84
	v_lshlrev_b32_e32 v36, 16, v85
	v_and_b32_e32 v37, 0xffff0000, v85
	v_lshlrev_b32_e32 v38, 16, v86
	v_and_b32_e32 v39, 0xffff0000, v86
	v_lshlrev_b32_e32 v40, 16, v87
	v_and_b32_e32 v41, 0xffff0000, v87
	v_lshlrev_b32_e32 v42, 16, v88
	v_and_b32_e32 v43, 0xffff0000, v88
	v_lshlrev_b32_e32 v44, 16, v89
	v_and_b32_e32 v45, 0xffff0000, v89
	v_lshlrev_b32_e32 v46, 16, v90
	v_and_b32_e32 v47, 0xffff0000, v90
	v_lshlrev_b32_e32 v48, 16, v91
	v_and_b32_e32 v49, 0xffff0000, v91
	v_pk_mul_f32 v[50:51], v[34:35], v[34:35]
	v_pk_fma_f32 v[50:51], v[36:37], v[36:37], v[50:51]
	v_pk_fma_f32 v[50:51], v[38:39], v[38:39], v[50:51]
	v_pk_fma_f32 v[50:51], v[40:41], v[40:41], v[50:51]
	v_pk_fma_f32 v[50:51], v[42:43], v[42:43], v[50:51]
	v_pk_fma_f32 v[50:51], v[44:45], v[44:45], v[50:51]
	v_pk_fma_f32 v[50:51], v[46:47], v[46:47], v[50:51]
	v_pk_fma_f32 v[50:51], v[48:49], v[48:49], v[50:51]
	v_add_f32_e32 v52, v50, v51
	s_nop 1
	v_add_f32_dpp v52, v52, v52 quad_perm:[1,0,3,2] row_mask:0xf bank_mask:0xf bound_ctrl:1
	s_nop 1
	v_add_f32_dpp v52, v52, v52 quad_perm:[2,3,0,1] row_mask:0xf bank_mask:0xf bound_ctrl:1
	s_nop 1
	v_add_f32_dpp v52, v52, v52 row_half_mirror row_mask:0xf bank_mask:0xf bound_ctrl:1
	s_nop 1
	v_add_f32_dpp v52, v52, v52 row_mirror row_mask:0xf bank_mask:0xf bound_ctrl:1
	s_nop 1
	v_readlane_b32 s28, v52, 16
	v_readlane_b32 s29, v52, 48
	v_readlane_b32 s24, v52, 0
	v_readlane_b32 s25, v52, 32
	s_nop 1
	v_mov_b32_e32 v52, s28
	v_mov_b32_e32 v53, s29
	v_pk_add_f32 v[52:53], s[24:25], v[52:53]
	s_nop 0
	v_add_f32_e32 v52, v52, v53
	v_fmamk_f32 v52, v52, 0x3a800000, v29
	v_rsq_f32_e32 v54, v52
	s_nop 0
	v_pk_mul_f32 v[56:57], v[54:55], v[34:35] op_sel_hi:[0,1]
	v_pk_mul_f32 v[164:165], v[6:7], v[56:57]
	v_pk_mul_f32 v[56:57], v[54:55], v[36:37] op_sel_hi:[0,1]
	v_pk_mul_f32 v[166:167], v[8:9], v[56:57]
	v_pk_mul_f32 v[56:57], v[54:55], v[38:39] op_sel_hi:[0,1]
	v_pk_mul_f32 v[168:169], v[2:3], v[56:57]
	v_pk_mul_f32 v[56:57], v[54:55], v[40:41] op_sel_hi:[0,1]
	v_pk_mul_f32 v[170:171], v[4:5], v[56:57]
	v_pk_mul_f32 v[56:57], v[54:55], v[42:43] op_sel_hi:[0,1]
	v_pk_mul_f32 v[172:173], v[14:15], v[56:57]
	v_pk_mul_f32 v[56:57], v[54:55], v[44:45] op_sel_hi:[0,1]
	v_pk_mul_f32 v[174:175], v[16:17], v[56:57]
	v_pk_mul_f32 v[56:57], v[54:55], v[46:47] op_sel_hi:[0,1]
	v_pk_mul_f32 v[176:177], v[10:11], v[56:57]
	v_pk_mul_f32 v[56:57], v[54:55], v[48:49] op_sel_hi:[0,1]
	v_pk_mul_f32 v[178:179], v[12:13], v[56:57]
	v_max3_f32 v58, |v164|, 0, |v165|
	v_max3_f32 v58, v58, |v166|, |v167|
	v_max3_f32 v58, v58, |v168|, |v169|
	v_max3_f32 v58, v58, |v170|, |v171|
	v_max3_f32 v58, v58, |v172|, |v173|
	v_max3_f32 v58, v58, |v174|, |v175|
	v_max3_f32 v58, v58, |v176|, |v177|
	v_max3_f32 v58, v58, |v178|, |v179|
	v_cvt_pk_bf16_f32 v62, v164, v165
	v_cvt_pk_bf16_f32 v63, v166, v167
	v_cvt_pk_bf16_f32 v64, v168, v169
	v_cvt_pk_bf16_f32 v65, v170, v171
	v_cvt_pk_bf16_f32 v66, v172, v173
	v_cvt_pk_bf16_f32 v67, v174, v175
	v_cvt_pk_bf16_f32 v68, v176, v177
	v_cvt_pk_bf16_f32 v69, v178, v179
	buffer_store_dwordx4 v[62:65], v26, s[12:15], 0 offen sc1
	buffer_store_dwordx4 v[66:69], v26, s[12:15], 0 offen offset:1024 sc1
	s_nop 1
	v_max_f32_dpp v58, v58, v58 quad_perm:[1,0,3,2] row_mask:0xf bank_mask:0xf
	s_nop 1
	v_max_f32_dpp v58, v58, v58 quad_perm:[2,3,0,1] row_mask:0xf bank_mask:0xf
; __device__ __forceinline__ void xn2_rows(const bf16* __restrict__ hb, const float* __restrict__ g, bf16* __restrict__ outp, unsigned char* __restrict__ xq, float* __restrict__ xs, int gwave, int nwaves, int lane, int rend) {
;     ...
;         mx = wave_max_dpp(mx);
;         const float sc = mx > 0.f ? mx * (1.f / 119.f) : 1.f, inv = 1.f / sc;
;         int sx = 0; unsigned W[4];
; #pragma unroll
;         for (int j = 0; j < 2; ++j) { unsigned wh = 0u, wl = 0u;
; #pragma unroll
;             for (int e = 0; e < 8; ++e) { const int q = (int)rintf(y[j][e] * inv); sx += q; const unsigned tq = (unsigned)(q + 8);
;                 wl |= ((tq & 15u) ^ 8u) << (4 * e); wh |= (((unsigned)((int)tq >> 4)) & 15u) << (4 * e); }
;             W[j] = wh; W[2 + j] = wl; }
;         { const bool o1 = (lane & 1) != 0, o2 = (lane & 2) != 0;
; #pragma unroll
;           for (int p = 0; p < 4; p += 2) { const unsigned t = o1 ? W[p] : W[p + 1]; const unsigned rc = (unsigned)__builtin_amdgcn_update_dpp(0, (int)t, 0xB1, 0xf, 0xf, false); if (o1) W[p] = rc; else W[p + 1] = rc; }
; #pragma unroll
;           for (int p = 0; p < 2; ++p) { const unsigned t = o2 ? W[p] : W[p + 2]; const unsigned rc = (unsigned)__builtin_amdgcn_update_dpp(0, (int)t, 0x4E, 0xf, 0xf, false); if (o2) W[p] = rc; else W[p + 2] = rc; } }
;         { const int m = lane & 3; v4u pw; pw.x = W[0]; pw.y = W[1]; pw.z = W[2]; pw.w = W[3];
;           __builtin_amdgcn_raw_buffer_store_b128(pw, rsQ, (int)((m & 2 ? 8u * (unsigned)MiB : 0u) + (unsigned)row * 512u + (unsigned)(m & 1) * 256u + 16u * (unsigned)(lane >> 2)), 0, 16); }
;         sx = wave_sum_dpp_i(sx);
;         if (lane == 0) { __hip_atomic_store(xs + row, sc, __ATOMIC_RELAXED, __HIP_MEMORY_SCOPE_AGENT); __hip_atomic_store((int*)(xs + T) + row, sx, __ATOMIC_RELAXED, __HIP_MEMORY_SCOPE_AGENT); }
	s_nop 1
	v_max_f32_dpp v58, v58, v58 row_half_mirror row_mask:0xf bank_mask:0xf
	s_nop 1
	v_max_f32_dpp v58, v58, v58 row_mirror row_mask:0xf bank_mask:0xf
	s_nop 1
	v_readlane_b32 s28, v58, 32
	v_readlane_b32 s29, v58, 48
	v_readlane_b32 s24, v58, 0
	v_readlane_b32 s25, v58, 16
	s_nop 1
	v_mov_b32_e32 v59, s29
	v_max_f32_e32 v59, s28, v59
	v_mov_b32_e32 v70, s25
	v_max3_f32 v59, s24, v70, v59
	v_mul_f32_e32 v70, 0x3c09ae41, v59
	v_cmp_lt_f32_e32 vcc, 0, v59
	s_nop 1
	v_cndmask_b32_e32 v59, 1.0, v70, vcc
	v_div_scale_f32 v70, s[24:25], v59, v59, 1.0
	v_rcp_f32_e32 v71, v70
	v_div_scale_f32 v72, vcc, 1.0, v59, 1.0
	v_fma_f32 v73, -v70, v71, 1.0
	v_fmac_f32_e32 v71, v73, v71
	v_mul_f32_e32 v73, v72, v71
	v_fma_f32 v74, -v70, v73, v72
	v_fmac_f32_e32 v73, v74, v71
	v_fma_f32 v70, -v70, v73, v72
	v_div_fmas_f32 v70, v70, v71, v73
	v_div_fixup_f32 v60, v70, v59, 1.0
	v_pk_mul_f32 v[56:57], v[60:61], v[164:165] op_sel_hi:[0,1]
	v_pk_add_f32 v[180:181], s[46:47], v[56:57]
	v_pk_mul_f32 v[56:57], v[60:61], v[166:167] op_sel_hi:[0,1]
	v_pk_add_f32 v[182:183], s[46:47], v[56:57]
	v_pk_mul_f32 v[56:57], v[60:61], v[168:169] op_sel_hi:[0,1]
	v_pk_add_f32 v[184:185], s[46:47], v[56:57]
	v_pk_mul_f32 v[56:57], v[60:61], v[170:171] op_sel_hi:[0,1]
	v_pk_add_f32 v[186:187], s[46:47], v[56:57]
	v_pk_mul_f32 v[56:57], v[60:61], v[172:173] op_sel_hi:[0,1]
	v_pk_add_f32 v[188:189], s[46:47], v[56:57]
	v_pk_mul_f32 v[56:57], v[60:61], v[174:175] op_sel_hi:[0,1]
	v_pk_add_f32 v[190:191], s[46:47], v[56:57]
	v_pk_mul_f32 v[56:57], v[60:61], v[176:177] op_sel_hi:[0,1]
	v_pk_add_f32 v[192:193], s[46:47], v[56:57]
	v_pk_mul_f32 v[56:57], v[60:61], v[178:179] op_sel_hi:[0,1]
	v_pk_add_f32 v[194:195], s[46:47], v[56:57]
	v_add3_u32 v208, v180, v181, v182
	v_add3_u32 v208, v208, v183, v184
	v_add3_u32 v208, v208, v185, v186
	v_add3_u32 v208, v208, v187, v188
	v_add3_u32 v208, v208, v189, v190
	v_add3_u32 v208, v208, v191, v192
	v_add3_u32 v208, v208, v193, v194
	v_add_u32_e32 v208, v208, v195
	v_add_u32_e32 v208, 0x4bffff80, v208
	v_perm_b32 v204, v182, v180, s48
	v_perm_b32 v205, v186, v184, s48
	v_perm_b32 v196, v205, v204, s49
	v_perm_b32 v204, v183, v181, s48
	v_perm_b32 v205, v187, v185, s48
	v_perm_b32 v197, v205, v204, s49
	v_lshlrev_b32_e32 v204, 4, v197
	v_lshrrev_b32_e32 v205, 4, v196
	v_bfi_b32 v202, s45, v196, v204
	v_bfi_b32 v200, s45, v205, v197
	v_xor_b32_e32 v202, 0x88888888, v202
	v_perm_b32 v204, v190, v188, s48
	v_perm_b32 v205, v194, v192, s48
	v_perm_b32 v196, v205, v204, s49
	v_perm_b32 v204, v191, v189, s48
	v_perm_b32 v205, v195, v193, s48
	v_perm_b32 v197, v205, v204, s49
	v_lshlrev_b32_e32 v204, 4, v197
	v_lshrrev_b32_e32 v205, 4, v196
	v_bfi_b32 v203, s45, v196, v204
	v_bfi_b32 v201, s45, v205, v197
	v_xor_b32_e32 v203, 0x88888888, v203
	v_cndmask_b32_e64 v204, v200, v201, s[4:5]
	v_cndmask_b32_e64 v205, v202, v203, s[4:5]
	s_nop 1
	v_mov_b32_dpp v206, v204 quad_perm:[1,0,3,2] row_mask:0xf bank_mask:0xf
	v_mov_b32_dpp v207, v205 quad_perm:[1,0,3,2] row_mask:0xf bank_mask:0xf
	s_nop 0
	v_cndmask_b32_e64 v200, v206, v200, s[4:5]
	v_cndmask_b32_e64 v201, v201, v206, s[4:5]
	v_cndmask_b32_e64 v202, v207, v202, s[4:5]
	v_cndmask_b32_e64 v203, v203, v207, s[4:5]
	v_cndmask_b32_e64 v204, v200, v202, s[6:7]
	v_cndmask_b32_e64 v205, v201, v203, s[6:7]
	s_nop 1
	v_mov_b32_dpp v206, v204 quad_perm:[2,3,0,1] row_mask:0xf bank_mask:0xf
	v_mov_b32_dpp v207, v205 quad_perm:[2,3,0,1] row_mask:0xf bank_mask:0xf
	s_nop 0
	v_cndmask_b32_e64 v200, v206, v200, s[6:7]
	v_cndmask_b32_e64 v202, v202, v206, s[6:7]
	v_cndmask_b32_e64 v201, v207, v201, s[6:7]
	v_cndmask_b32_e64 v203, v203, v207, s[6:7]
	buffer_store_dwordx4 v[200:203], v33, s[16:19], 0 offen sc1
	s_nop 1
	v_add_u32_dpp v208, v208, v208 quad_perm:[1,0,3,2] row_mask:0xf bank_mask:0xf bound_ctrl:1
	s_nop 1
	v_add_u32_dpp v208, v208, v208 quad_perm:[2,3,0,1] row_mask:0xf bank_mask:0xf bound_ctrl:1
	s_nop 1
	v_add_u32_dpp v208, v208, v208 row_half_mirror row_mask:0xf bank_mask:0xf bound_ctrl:1
	s_nop 1
	v_add_u32_dpp v208, v208, v208 row_mirror row_mask:0xf bank_mask:0xf bound_ctrl:1
	s_nop 1
	v_readlane_b32 s28, v208, 0
	v_readlane_b32 s29, v208, 16
	v_readlane_b32 s30, v208, 32
	v_readlane_b32 s31, v208, 48
	s_nop 1
	s_add_i32 s28, s29, s28
	s_add_i32 s28, s28, s30
	s_add_i32 s30, s28, s31
	s_and_saveexec_b64 s[24:25], s[8:9]
	global_store_dword v30, v59, s[98:99] sc1
	v_mov_b32_e32 v70, s30
	global_store_dword v31, v70, s[98:99] sc1
	s_mov_b64 exec, s[24:25]
	s_waitcnt vmcnt(17)
; __device__ __forceinline__ void xn2_rows(const bf16* __restrict__ hb, const float* __restrict__ g, bf16* __restrict__ outp, unsigned char* __restrict__ xq, float* __restrict__ xs, int gwave, int nwaves, int lane, int rend) {
;     ...
;     for (int row = gwave; row < rend; row += nwaves) {
;         const v4u* xb = (const v4u*)(hb + (size_t)row * D) + lane;
;         float v[2][8]; float ss = 0.f;
; #pragma unroll
;         for (int j = 0; j < 2; ++j) { const v4u w = xb[64 * j]; const unsigned ww[4] = {w.x, w.y, w.z, w.w};
; #pragma unroll
;             for (int e = 0; e < 4; ++e) { v[j][2 * e] = __uint_as_float(ww[e] << 16); v[j][2 * e + 1] = __uint_as_float(ww[e] & 0xffff0000u); ss += v[j][2 * e] * v[j][2 * e] + v[j][2 * e + 1] * v[j][2 * e + 1]; } }
;         ss = wave_sum(ss);
;         const float r = rsqrtf(ss * (1.f / D) + EPS);
;         float y[2][8]; float mx = 0.f;
; #pragma unroll
;         for (int j = 0; j < 2; ++j) { const float4 g0 = ((const float4*)g)[2 * lane + 128 * j], g1 = ((const float4*)g)[2 * lane + 128 * j + 1]; const float gg[8] = {g0.x, g0.y, g0.z, g0.w, g1.x, g1.y, g1.z, g1.w};
; #pragma unroll
;             for (int e = 0; e < 8; ++e) { y[j][e] = v[j][e] * r * gg[e]; mx = fmaxf(mx, fabsf(y[j][e])); }
;             v4u ow; ow.x = pk2(y[j][0], y[j][1]); ow.y = pk2(y[j][2], y[j][3]); ow.z = pk2(y[j][4], y[j][5]); ow.w = pk2(y[j][6], y[j][7]);
;             __builtin_amdgcn_raw_buffer_store_b128(ow, rsO, (int)(((unsigned)row * D + 8u * (unsigned)lane + 512u * j) * 2u), 0, 16); }
;         mx = wave_max_dpp(mx);
;         const float sc = mx > 0.f ? mx * (1.f / 119.f) : 1.f, inv = 1.f / sc;
;         int sx = 0; unsigned W[4];
; #pragma unroll
;         for (int j = 0; j < 2; ++j) { unsigned wh = 0u, wl = 0u;
; #pragma unroll
;             for (int e = 0; e < 8; ++e) { const int q = (int)rintf(y[j][e] * inv); sx += q; const unsigned tq = (unsigned)(q + 8);
	v_lshlrev_b32_e32 v34, 16, v92
	v_and_b32_e32 v35, 0xffff0000, v92
	v_lshlrev_b32_e32 v36, 16, v93
	v_and_b32_e32 v37, 0xffff0000, v93
	v_lshlrev_b32_e32 v38, 16, v94
	v_and_b32_e32 v39, 0xffff0000, v94
	v_lshlrev_b32_e32 v40, 16, v95
	v_and_b32_e32 v41, 0xffff0000, v95
	v_lshlrev_b32_e32 v42, 16, v96
	v_and_b32_e32 v43, 0xffff0000, v96
	v_lshlrev_b32_e32 v44, 16, v97
	v_and_b32_e32 v45, 0xffff0000, v97
	v_lshlrev_b32_e32 v46, 16, v98
	v_and_b32_e32 v47, 0xffff0000, v98
	v_lshlrev_b32_e32 v48, 16, v99
	v_and_b32_e32 v49, 0xffff0000, v99
	v_pk_mul_f32 v[50:51], v[34:35], v[34:35]
	v_pk_fma_f32 v[50:51], v[36:37], v[36:37], v[50:51]
	v_pk_fma_f32 v[50:51], v[38:39], v[38:39], v[50:51]
	v_pk_fma_f32 v[50:51], v[40:41], v[40:41], v[50:51]
	v_pk_fma_f32 v[50:51], v[42:43], v[42:43], v[50:51]
	v_pk_fma_f32 v[50:51], v[44:45], v[44:45], v[50:51]
	v_pk_fma_f32 v[50:51], v[46:47], v[46:47], v[50:51]
	v_pk_fma_f32 v[50:51], v[48:49], v[48:49], v[50:51]
	v_add_f32_e32 v52, v50, v51
	s_nop 1
	v_add_f32_dpp v52, v52, v52 quad_perm:[1,0,3,2] row_mask:0xf bank_mask:0xf bound_ctrl:1
	s_nop 1
	v_add_f32_dpp v52, v52, v52 quad_perm:[2,3,0,1] row_mask:0xf bank_mask:0xf bound_ctrl:1
	s_nop 1
	v_add_f32_dpp v52, v52, v52 row_half_mirror row_mask:0xf bank_mask:0xf bound_ctrl:1
	s_nop 1
	v_add_f32_dpp v52, v52, v52 row_mirror row_mask:0xf bank_mask:0xf bound_ctrl:1
	s_nop 1
	v_readlane_b32 s28, v52, 16
	v_readlane_b32 s29, v52, 48
	v_readlane_b32 s24, v52, 0
	v_readlane_b32 s25, v52, 32
	s_nop 1
	v_mov_b32_e32 v52, s28
	v_mov_b32_e32 v53, s29
	v_pk_add_f32 v[52:53], s[24:25], v[52:53]
	s_nop 0
	v_add_f32_e32 v52, v52, v53
	v_fmamk_f32 v52, v52, 0x3a800000, v29
	v_rsq_f32_e32 v54, v52
	s_nop 0
	v_pk_mul_f32 v[56:57], v[54:55], v[34:35] op_sel_hi:[0,1]
	v_pk_mul_f32 v[164:165], v[6:7], v[56:57]
	v_pk_mul_f32 v[56:57], v[54:55], v[36:37] op_sel_hi:[0,1]
	v_pk_mul_f32 v[166:167], v[8:9], v[56:57]
	v_pk_mul_f32 v[56:57], v[54:55], v[38:39] op_sel_hi:[0,1]
	v_pk_mul_f32 v[168:169], v[2:3], v[56:57]
	v_pk_mul_f32 v[56:57], v[54:55], v[40:41] op_sel_hi:[0,1]
	v_pk_mul_f32 v[170:171], v[4:5], v[56:57]
	v_pk_mul_f32 v[56:57], v[54:55], v[42:43] op_sel_hi:[0,1]
	v_pk_mul_f32 v[172:173], v[14:15], v[56:57]
	v_pk_mul_f32 v[56:57], v[54:55], v[44:45] op_sel_hi:[0,1]
	v_pk_mul_f32 v[174:175], v[16:17], v[56:57]
	v_pk_mul_f32 v[56:57], v[54:55], v[46:47] op_sel_hi:[0,1]
	v_pk_mul_f32 v[176:177], v[10:11], v[56:57]
	v_pk_mul_f32 v[56:57], v[54:55], v[48:49] op_sel_hi:[0,1]
	v_pk_mul_f32 v[178:179], v[12:13], v[56:57]
	v_max3_f32 v58, |v164|, 0, |v165|
	v_max3_f32 v58, v58, |v166|, |v167|
	v_max3_f32 v58, v58, |v168|, |v169|
	v_max3_f32 v58, v58, |v170|, |v171|
	v_max3_f32 v58, v58, |v172|, |v173|
	v_max3_f32 v58, v58, |v174|, |v175|
	v_max3_f32 v58, v58, |v176|, |v177|
	v_max3_f32 v58, v58, |v178|, |v179|
	v_cvt_pk_bf16_f32 v62, v164, v165
	v_cvt_pk_bf16_f32 v63, v166, v167
	v_cvt_pk_bf16_f32 v64, v168, v169
	v_cvt_pk_bf16_f32 v65, v170, v171
	v_cvt_pk_bf16_f32 v66, v172, v173
	v_cvt_pk_bf16_f32 v67, v174, v175
	v_cvt_pk_bf16_f32 v68, v176, v177
	v_cvt_pk_bf16_f32 v69, v178, v179
	v_add_u32_e32 v209, 0x4000, v26
	buffer_store_dwordx4 v[62:65], v209, s[12:15], 0 offen sc1
	buffer_store_dwordx4 v[66:69], v209, s[12:15], 0 offen offset:1024 sc1
	s_nop 1
	v_max_f32_dpp v58, v58, v58 quad_perm:[1,0,3,2] row_mask:0xf bank_mask:0xf
	s_nop 1
	v_max_f32_dpp v58, v58, v58 quad_perm:[2,3,0,1] row_mask:0xf bank_mask:0xf
	s_nop 1
	v_max_f32_dpp v58, v58, v58 row_half_mirror row_mask:0xf bank_mask:0xf
	s_nop 1
	v_max_f32_dpp v58, v58, v58 row_mirror row_mask:0xf bank_mask:0xf
	s_nop 1
	v_readlane_b32 s28, v58, 32
	v_readlane_b32 s29, v58, 48
	v_readlane_b32 s24, v58, 0
	v_readlane_b32 s25, v58, 16
	s_nop 1
	v_mov_b32_e32 v59, s29
	v_max_f32_e32 v59, s28, v59
	v_mov_b32_e32 v70, s25
	v_max3_f32 v59, s24, v70, v59
	v_mul_f32_e32 v70, 0x3c09ae41, v59
	v_cmp_lt_f32_e32 vcc, 0, v59
	s_nop 1
	v_cndmask_b32_e32 v59, 1.0, v70, vcc
	v_div_scale_f32 v70, s[24:25], v59, v59, 1.0
	v_rcp_f32_e32 v71, v70
	v_div_scale_f32 v72, vcc, 1.0, v59, 1.0
	v_fma_f32 v73, -v70, v71, 1.0
	v_fmac_f32_e32 v71, v73, v71
	v_mul_f32_e32 v73, v72, v71
	v_fma_f32 v74, -v70, v73, v72
	v_fmac_f32_e32 v73, v74, v71
	v_fma_f32 v70, -v70, v73, v72
	v_div_fmas_f32 v70, v70, v71, v73
	v_div_fixup_f32 v60, v70, v59, 1.0
	v_pk_mul_f32 v[56:57], v[60:61], v[164:165] op_sel_hi:[0,1]
	v_pk_add_f32 v[180:181], s[46:47], v[56:57]
	v_pk_mul_f32 v[56:57], v[60:61], v[166:167] op_sel_hi:[0,1]
	v_pk_add_f32 v[182:183], s[46:47], v[56:57]
	v_pk_mul_f32 v[56:57], v[60:61], v[168:169] op_sel_hi:[0,1]
	v_pk_add_f32 v[184:185], s[46:47], v[56:57]
	v_pk_mul_f32 v[56:57], v[60:61], v[170:171] op_sel_hi:[0,1]
	v_pk_add_f32 v[186:187], s[46:47], v[56:57]
	v_pk_mul_f32 v[56:57], v[60:61], v[172:173] op_sel_hi:[0,1]
	v_pk_add_f32 v[188:189], s[46:47], v[56:57]
	v_pk_mul_f32 v[56:57], v[60:61], v[174:175] op_sel_hi:[0,1]
	v_pk_add_f32 v[190:191], s[46:47], v[56:57]
	v_pk_mul_f32 v[56:57], v[60:61], v[176:177] op_sel_hi:[0,1]
	v_pk_add_f32 v[192:193], s[46:47], v[56:57]
	v_pk_mul_f32 v[56:57], v[60:61], v[178:179] op_sel_hi:[0,1]
	v_pk_add_f32 v[194:195], s[46:47], v[56:57]
	v_add3_u32 v208, v180, v181, v182
	v_add3_u32 v208, v208, v183, v184
	v_add3_u32 v208, v208, v185, v186
	v_add3_u32 v208, v208, v187, v188
	v_add3_u32 v208, v208, v189, v190
	v_add3_u32 v208, v208, v191, v192
	v_add3_u32 v208, v208, v193, v194
	v_add_u32_e32 v208, v208, v195
	v_add_u32_e32 v208, 0x4bffff80, v208
	v_perm_b32 v204, v182, v180, s48
	v_perm_b32 v205, v186, v184, s48
	v_perm_b32 v196, v205, v204, s49
	v_perm_b32 v204, v183, v181, s48
	v_perm_b32 v205, v187, v185, s48
; __device__ __forceinline__ void xn2_rows(const bf16* __restrict__ hb, const float* __restrict__ g, bf16* __restrict__ outp, unsigned char* __restrict__ xq, float* __restrict__ xs, int gwave, int nwaves, int lane, int rend) {
;     ...
;         const v4u* xb = (const v4u*)(hb + (size_t)row * D) + lane;
;         float v[2][8]; float ss = 0.f;
; #pragma unroll
;         for (int j = 0; j < 2; ++j) { const v4u w = xb[64 * j]; const unsigned ww[4] = {w.x, w.y, w.z, w.w};
; #pragma unroll
;             for (int e = 0; e < 4; ++e) { v[j][2 * e] = __uint_as_float(ww[e] << 16); v[j][2 * e + 1] = __uint_as_float(ww[e] & 0xffff0000u); ss += v[j][2 * e] * v[j][2 * e] + v[j][2 * e + 1] * v[j][2 * e + 1]; } }
;         ss = wave_sum(ss);
;         const float r = rsqrtf(ss * (1.f / D) + EPS);
;         float y[2][8]; float mx = 0.f;
; #pragma unroll
;         for (int j = 0; j < 2; ++j) { const float4 g0 = ((const float4*)g)[2 * lane + 128 * j], g1 = ((const float4*)g)[2 * lane + 128 * j + 1]; const float gg[8] = {g0.x, g0.y, g0.z, g0.w, g1.x, g1.y, g1.z, g1.w};
; #pragma unroll
;             for (int e = 0; e < 8; ++e) { y[j][e] = v[j][e] * r * gg[e]; mx = fmaxf(mx, fabsf(y[j][e])); }
;             v4u ow; ow.x = pk2(y[j][0], y[j][1]); ow.y = pk2(y[j][2], y[j][3]); ow.z = pk2(y[j][4], y[j][5]); ow.w = pk2(y[j][6], y[j][7]);
;             __builtin_amdgcn_raw_buffer_store_b128(ow, rsO, (int)(((unsigned)row * D + 8u * (unsigned)lane + 512u * j) * 2u), 0, 16); }
;         mx = wave_max_dpp(mx);
;         const float sc = mx > 0.f ? mx * (1.f / 119.f) : 1.f, inv = 1.f / sc;
;         int sx = 0; unsigned W[4];
; #pragma unroll
;         for (int j = 0; j < 2; ++j) { unsigned wh = 0u, wl = 0u;
; #pragma unroll
;             for (int e = 0; e < 8; ++e) { const int q = (int)rintf(y[j][e] * inv); sx += q; const unsigned tq = (unsigned)(q + 8);
;                 wl |= ((tq & 15u) ^ 8u) << (4 * e); wh |= (((unsigned)((int)tq >> 4)) & 15u) << (4 * e); }
;             W[j] = wh; W[2 + j] = wl; }
;         { const bool o1 = (lane & 1) != 0, o2 = (lane & 2) != 0;
; #pragma unroll
;           for (int p = 0; p < 4; p += 2) { const unsigned t = o1 ? W[p] : W[p + 1]; const unsigned rc = (unsigned)__builtin_amdgcn_update_dpp(0, (int)t, 0xB1, 0xf, 0xf, false); if (o1) W[p] = rc; else W[p + 1] = rc; }
; #pragma unroll
	v_perm_b32 v197, v205, v204, s49
	v_lshlrev_b32_e32 v204, 4, v197
	v_lshrrev_b32_e32 v205, 4, v196
	v_bfi_b32 v202, s45, v196, v204
	v_bfi_b32 v200, s45, v205, v197
	v_xor_b32_e32 v202, 0x88888888, v202
	v_perm_b32 v204, v190, v188, s48
	v_perm_b32 v205, v194, v192, s48
	v_perm_b32 v196, v205, v204, s49
	v_perm_b32 v204, v191, v189, s48
	v_perm_b32 v205, v195, v193, s48
	v_perm_b32 v197, v205, v204, s49
	v_lshlrev_b32_e32 v204, 4, v197
	v_lshrrev_b32_e32 v205, 4, v196
	v_bfi_b32 v203, s45, v196, v204
	v_bfi_b32 v201, s45, v205, v197
	v_xor_b32_e32 v203, 0x88888888, v203
	v_cndmask_b32_e64 v204, v200, v201, s[4:5]
	v_cndmask_b32_e64 v205, v202, v203, s[4:5]
	s_nop 1
	v_mov_b32_dpp v206, v204 quad_perm:[1,0,3,2] row_mask:0xf bank_mask:0xf
	v_mov_b32_dpp v207, v205 quad_perm:[1,0,3,2] row_mask:0xf bank_mask:0xf
	s_nop 0
	v_cndmask_b32_e64 v200, v206, v200, s[4:5]
	v_cndmask_b32_e64 v201, v201, v206, s[4:5]
	v_cndmask_b32_e64 v202, v207, v202, s[4:5]
	v_cndmask_b32_e64 v203, v203, v207, s[4:5]
	v_cndmask_b32_e64 v204, v200, v202, s[6:7]
	v_cndmask_b32_e64 v205, v201, v203, s[6:7]
	s_nop 1
	v_mov_b32_dpp v206, v204 quad_perm:[2,3,0,1] row_mask:0xf bank_mask:0xf
	v_mov_b32_dpp v207, v205 quad_perm:[2,3,0,1] row_mask:0xf bank_mask:0xf
	s_nop 0
	v_cndmask_b32_e64 v200, v206, v200, s[6:7]
	v_cndmask_b32_e64 v202, v202, v206, s[6:7]
	v_cndmask_b32_e64 v201, v207, v201, s[6:7]
	v_cndmask_b32_e64 v203, v203, v207, s[6:7]
	v_add_u32_e32 v209, 0x1000, v33
	buffer_store_dwordx4 v[200:203], v209, s[16:19], 0 offen sc1
	s_nop 1
	v_add_u32_dpp v208, v208, v208 quad_perm:[1,0,3,2] row_mask:0xf bank_mask:0xf bound_ctrl:1
	s_nop 1
	v_add_u32_dpp v208, v208, v208 quad_perm:[2,3,0,1] row_mask:0xf bank_mask:0xf bound_ctrl:1
	s_nop 1
	v_add_u32_dpp v208, v208, v208 row_half_mirror row_mask:0xf bank_mask:0xf bound_ctrl:1
	s_nop 1
	v_add_u32_dpp v208, v208, v208 row_mirror row_mask:0xf bank_mask:0xf bound_ctrl:1
	s_nop 1
	v_readlane_b32 s28, v208, 0
	v_readlane_b32 s29, v208, 16
	v_readlane_b32 s30, v208, 32
	v_readlane_b32 s31, v208, 48
	s_nop 1
	s_add_i32 s28, s29, s28
	s_add_i32 s28, s28, s30
	s_add_i32 s30, s28, s31
	s_and_saveexec_b64 s[24:25], s[8:9]
	global_store_dword v30, v59, s[98:99] offset:32 sc1
	v_mov_b32_e32 v70, s30
	global_store_dword v31, v70, s[98:99] offset:32 sc1
	s_mov_b64 exec, s[24:25]
	s_waitcnt vmcnt(20)
	v_lshlrev_b32_e32 v34, 16, v100
	v_and_b32_e32 v35, 0xffff0000, v100
	v_lshlrev_b32_e32 v36, 16, v101
	v_and_b32_e32 v37, 0xffff0000, v101
	v_lshlrev_b32_e32 v38, 16, v102
	v_and_b32_e32 v39, 0xffff0000, v102
	v_lshlrev_b32_e32 v40, 16, v103
	v_and_b32_e32 v41, 0xffff0000, v103
	v_lshlrev_b32_e32 v42, 16, v104
	v_and_b32_e32 v43, 0xffff0000, v104
	v_lshlrev_b32_e32 v44, 16, v105
	v_and_b32_e32 v45, 0xffff0000, v105
	v_lshlrev_b32_e32 v46, 16, v106
	v_and_b32_e32 v47, 0xffff0000, v106
	v_lshlrev_b32_e32 v48, 16, v107
	v_and_b32_e32 v49, 0xffff0000, v107
	v_pk_mul_f32 v[50:51], v[34:35], v[34:35]
	v_pk_fma_f32 v[50:51], v[36:37], v[36:37], v[50:51]
	v_pk_fma_f32 v[50:51], v[38:39], v[38:39], v[50:51]
	v_pk_fma_f32 v[50:51], v[40:41], v[40:41], v[50:51]
	v_pk_fma_f32 v[50:51], v[42:43], v[42:43], v[50:51]
	v_pk_fma_f32 v[50:51], v[44:45], v[44:45], v[50:51]
	v_pk_fma_f32 v[50:51], v[46:47], v[46:47], v[50:51]
	v_pk_fma_f32 v[50:51], v[48:49], v[48:49], v[50:51]
	v_add_f32_e32 v52, v50, v51
	s_nop 1
	v_add_f32_dpp v52, v52, v52 quad_perm:[1,0,3,2] row_mask:0xf bank_mask:0xf bound_ctrl:1
	s_nop 1
	v_add_f32_dpp v52, v52, v52 quad_perm:[2,3,0,1] row_mask:0xf bank_mask:0xf bound_ctrl:1
	s_nop 1
	v_add_f32_dpp v52, v52, v52 row_half_mirror row_mask:0xf bank_mask:0xf bound_ctrl:1
	s_nop 1
	v_add_f32_dpp v52, v52, v52 row_mirror row_mask:0xf bank_mask:0xf bound_ctrl:1
	s_nop 1
	v_readlane_b32 s28, v52, 16
	v_readlane_b32 s29, v52, 48
	v_readlane_b32 s24, v52, 0
	v_readlane_b32 s25, v52, 32
	s_nop 1
	v_mov_b32_e32 v52, s28
	v_mov_b32_e32 v53, s29
	v_pk_add_f32 v[52:53], s[24:25], v[52:53]
	s_nop 0
	v_add_f32_e32 v52, v52, v53
	v_fmamk_f32 v52, v52, 0x3a800000, v29
	v_rsq_f32_e32 v54, v52
	s_nop 0
	v_pk_mul_f32 v[56:57], v[54:55], v[34:35] op_sel_hi:[0,1]
	v_pk_mul_f32 v[164:165], v[6:7], v[56:57]
	v_pk_mul_f32 v[56:57], v[54:55], v[36:37] op_sel_hi:[0,1]
	v_pk_mul_f32 v[166:167], v[8:9], v[56:57]
	v_pk_mul_f32 v[56:57], v[54:55], v[38:39] op_sel_hi:[0,1]
	v_pk_mul_f32 v[168:169], v[2:3], v[56:57]
	v_pk_mul_f32 v[56:57], v[54:55], v[40:41] op_sel_hi:[0,1]
	v_pk_mul_f32 v[170:171], v[4:5], v[56:57]
	v_pk_mul_f32 v[56:57], v[54:55], v[42:43] op_sel_hi:[0,1]
	v_pk_mul_f32 v[172:173], v[14:15], v[56:57]
	v_pk_mul_f32 v[56:57], v[54:55], v[44:45] op_sel_hi:[0,1]
	v_pk_mul_f32 v[174:175], v[16:17], v[56:57]
	v_pk_mul_f32 v[56:57], v[54:55], v[46:47] op_sel_hi:[0,1]
	v_pk_mul_f32 v[176:177], v[10:11], v[56:57]
	v_pk_mul_f32 v[56:57], v[54:55], v[48:49] op_sel_hi:[0,1]
	v_pk_mul_f32 v[178:179], v[12:13], v[56:57]
	v_max3_f32 v58, |v164|, 0, |v165|
	v_max3_f32 v58, v58, |v166|, |v167|
	v_max3_f32 v58, v58, |v168|, |v169|
	v_max3_f32 v58, v58, |v170|, |v171|
	v_max3_f32 v58, v58, |v172|, |v173|
	v_max3_f32 v58, v58, |v174|, |v175|
	v_max3_f32 v58, v58, |v176|, |v177|
	v_max3_f32 v58, v58, |v178|, |v179|
	v_cvt_pk_bf16_f32 v62, v164, v165
	v_cvt_pk_bf16_f32 v63, v166, v167
	v_cvt_pk_bf16_f32 v64, v168, v169
	v_cvt_pk_bf16_f32 v65, v170, v171
	v_cvt_pk_bf16_f32 v66, v172, v173
	v_cvt_pk_bf16_f32 v67, v174, v175
	v_cvt_pk_bf16_f32 v68, v176, v177
	v_cvt_pk_bf16_f32 v69, v178, v179
	v_add_u32_e32 v209, 0x8000, v26
	buffer_store_dwordx4 v[62:65], v209, s[12:15], 0 offen sc1
	buffer_store_dwordx4 v[66:69], v209, s[12:15], 0 offen offset:1024 sc1
	s_nop 1
; __device__ __forceinline__ void xn2_rows(const bf16* __restrict__ hb, const float* __restrict__ g, bf16* __restrict__ outp, unsigned char* __restrict__ xq, float* __restrict__ xs, int gwave, int nwaves, int lane, int rend) {
;     ...
;         mx = wave_max_dpp(mx);
;         const float sc = mx > 0.f ? mx * (1.f / 119.f) : 1.f, inv = 1.f / sc;
;         int sx = 0; unsigned W[4];
; #pragma unroll
;         for (int j = 0; j < 2; ++j) { unsigned wh = 0u, wl = 0u;
; #pragma unroll
;             for (int e = 0; e < 8; ++e) { const int q = (int)rintf(y[j][e] * inv); sx += q; const unsigned tq = (unsigned)(q + 8);
;                 wl |= ((tq & 15u) ^ 8u) << (4 * e); wh |= (((unsigned)((int)tq >> 4)) & 15u) << (4 * e); }
;             W[j] = wh; W[2 + j] = wl; }
;         { const bool o1 = (lane & 1) != 0, o2 = (lane & 2) != 0;
; #pragma unroll
;           for (int p = 0; p < 4; p += 2) { const unsigned t = o1 ? W[p] : W[p + 1]; const unsigned rc = (unsigned)__builtin_amdgcn_update_dpp(0, (int)t, 0xB1, 0xf, 0xf, false); if (o1) W[p] = rc; else W[p + 1] = rc; }
; #pragma unroll
;           for (int p = 0; p < 2; ++p) { const unsigned t = o2 ? W[p] : W[p + 2]; const unsigned rc = (unsigned)__builtin_amdgcn_update_dpp(0, (int)t, 0x4E, 0xf, 0xf, false); if (o2) W[p] = rc; else W[p + 2] = rc; } }
;         { const int m = lane & 3; v4u pw; pw.x = W[0]; pw.y = W[1]; pw.z = W[2]; pw.w = W[3];
;           __builtin_amdgcn_raw_buffer_store_b128(pw, rsQ, (int)((m & 2 ? 8u * (unsigned)MiB : 0u) + (unsigned)row * 512u + (unsigned)(m & 1) * 256u + 16u * (unsigned)(lane >> 2)), 0, 16); }
;         sx = wave_sum_dpp_i(sx);
;         if (lane == 0) { __hip_atomic_store(xs + row, sc, __ATOMIC_RELAXED, __HIP_MEMORY_SCOPE_AGENT); __hip_atomic_store((int*)(xs + T) + row, sx, __ATOMIC_RELAXED, __HIP_MEMORY_SCOPE_AGENT); }
	v_max_f32_dpp v58, v58, v58 quad_perm:[1,0,3,2] row_mask:0xf bank_mask:0xf
	s_nop 1
	v_max_f32_dpp v58, v58, v58 quad_perm:[2,3,0,1] row_mask:0xf bank_mask:0xf
	s_nop 1
	v_max_f32_dpp v58, v58, v58 row_half_mirror row_mask:0xf bank_mask:0xf
	s_nop 1
	v_max_f32_dpp v58, v58, v58 row_mirror row_mask:0xf bank_mask:0xf
	s_nop 1
	v_readlane_b32 s28, v58, 32
	v_readlane_b32 s29, v58, 48
	v_readlane_b32 s24, v58, 0
	v_readlane_b32 s25, v58, 16
	s_nop 1
	v_mov_b32_e32 v59, s29
	v_max_f32_e32 v59, s28, v59
	v_mov_b32_e32 v70, s25
	v_max3_f32 v59, s24, v70, v59
	v_mul_f32_e32 v70, 0x3c09ae41, v59
	v_cmp_lt_f32_e32 vcc, 0, v59
	s_nop 1
	v_cndmask_b32_e32 v59, 1.0, v70, vcc
	v_div_scale_f32 v70, s[24:25], v59, v59, 1.0
	v_rcp_f32_e32 v71, v70
	v_div_scale_f32 v72, vcc, 1.0, v59, 1.0
	v_fma_f32 v73, -v70, v71, 1.0
	v_fmac_f32_e32 v71, v73, v71
	v_mul_f32_e32 v73, v72, v71
	v_fma_f32 v74, -v70, v73, v72
	v_fmac_f32_e32 v73, v74, v71
	v_fma_f32 v70, -v70, v73, v72
	v_div_fmas_f32 v70, v70, v71, v73
	v_div_fixup_f32 v60, v70, v59, 1.0
	v_pk_mul_f32 v[56:57], v[60:61], v[164:165] op_sel_hi:[0,1]
	v_pk_add_f32 v[180:181], s[46:47], v[56:57]
	v_pk_mul_f32 v[56:57], v[60:61], v[166:167] op_sel_hi:[0,1]
	v_pk_add_f32 v[182:183], s[46:47], v[56:57]
	v_pk_mul_f32 v[56:57], v[60:61], v[168:169] op_sel_hi:[0,1]
	v_pk_add_f32 v[184:185], s[46:47], v[56:57]
	v_pk_mul_f32 v[56:57], v[60:61], v[170:171] op_sel_hi:[0,1]
	v_pk_add_f32 v[186:187], s[46:47], v[56:57]
	v_pk_mul_f32 v[56:57], v[60:61], v[172:173] op_sel_hi:[0,1]
	v_pk_add_f32 v[188:189], s[46:47], v[56:57]
	v_pk_mul_f32 v[56:57], v[60:61], v[174:175] op_sel_hi:[0,1]
	v_pk_add_f32 v[190:191], s[46:47], v[56:57]
	v_pk_mul_f32 v[56:57], v[60:61], v[176:177] op_sel_hi:[0,1]
	v_pk_add_f32 v[192:193], s[46:47], v[56:57]
	v_pk_mul_f32 v[56:57], v[60:61], v[178:179] op_sel_hi:[0,1]
	v_pk_add_f32 v[194:195], s[46:47], v[56:57]
	v_add3_u32 v208, v180, v181, v182
	v_add3_u32 v208, v208, v183, v184
	v_add3_u32 v208, v208, v185, v186
	v_add3_u32 v208, v208, v187, v188
	v_add3_u32 v208, v208, v189, v190
	v_add3_u32 v208, v208, v191, v192
	v_add3_u32 v208, v208, v193, v194
	v_add_u32_e32 v208, v208, v195
	v_add_u32_e32 v208, 0x4bffff80, v208
	v_perm_b32 v204, v182, v180, s48
	v_perm_b32 v205, v186, v184, s48
	v_perm_b32 v196, v205, v204, s49
	v_perm_b32 v204, v183, v181, s48
	v_perm_b32 v205, v187, v185, s48
	v_perm_b32 v197, v205, v204, s49
	v_lshlrev_b32_e32 v204, 4, v197
	v_lshrrev_b32_e32 v205, 4, v196
	v_bfi_b32 v202, s45, v196, v204
	v_bfi_b32 v200, s45, v205, v197
	v_xor_b32_e32 v202, 0x88888888, v202
	v_perm_b32 v204, v190, v188, s48
	v_perm_b32 v205, v194, v192, s48
	v_perm_b32 v196, v205, v204, s49
	v_perm_b32 v204, v191, v189, s48
	v_perm_b32 v205, v195, v193, s48
	v_perm_b32 v197, v205, v204, s49
	v_lshlrev_b32_e32 v204, 4, v197
	v_lshrrev_b32_e32 v205, 4, v196
	v_bfi_b32 v203, s45, v196, v204
	v_bfi_b32 v201, s45, v205, v197
	v_xor_b32_e32 v203, 0x88888888, v203
	v_cndmask_b32_e64 v204, v200, v201, s[4:5]
	v_cndmask_b32_e64 v205, v202, v203, s[4:5]
	s_nop 1
	v_mov_b32_dpp v206, v204 quad_perm:[1,0,3,2] row_mask:0xf bank_mask:0xf
	v_mov_b32_dpp v207, v205 quad_perm:[1,0,3,2] row_mask:0xf bank_mask:0xf
	s_nop 0
	v_cndmask_b32_e64 v200, v206, v200, s[4:5]
	v_cndmask_b32_e64 v201, v201, v206, s[4:5]
	v_cndmask_b32_e64 v202, v207, v202, s[4:5]
	v_cndmask_b32_e64 v203, v203, v207, s[4:5]
	v_cndmask_b32_e64 v204, v200, v202, s[6:7]
	v_cndmask_b32_e64 v205, v201, v203, s[6:7]
	s_nop 1
	v_mov_b32_dpp v206, v204 quad_perm:[2,3,0,1] row_mask:0xf bank_mask:0xf
	v_mov_b32_dpp v207, v205 quad_perm:[2,3,0,1] row_mask:0xf bank_mask:0xf
	s_nop 0
	v_cndmask_b32_e64 v200, v206, v200, s[6:7]
	v_cndmask_b32_e64 v202, v202, v206, s[6:7]
	v_cndmask_b32_e64 v201, v207, v201, s[6:7]
	v_cndmask_b32_e64 v203, v203, v207, s[6:7]
	v_add_u32_e32 v209, 0x2000, v33
	buffer_store_dwordx4 v[200:203], v209, s[16:19], 0 offen sc1
	s_nop 1
	v_add_u32_dpp v208, v208, v208 quad_perm:[1,0,3,2] row_mask:0xf bank_mask:0xf bound_ctrl:1
	s_nop 1
	v_add_u32_dpp v208, v208, v208 quad_perm:[2,3,0,1] row_mask:0xf bank_mask:0xf bound_ctrl:1
	s_nop 1
	v_add_u32_dpp v208, v208, v208 row_half_mirror row_mask:0xf bank_mask:0xf bound_ctrl:1
	s_nop 1
	v_add_u32_dpp v208, v208, v208 row_mirror row_mask:0xf bank_mask:0xf bound_ctrl:1
	s_nop 1
	v_readlane_b32 s28, v208, 0
	v_readlane_b32 s29, v208, 16
	v_readlane_b32 s30, v208, 32
	v_readlane_b32 s31, v208, 48
	s_nop 1
	s_add_i32 s28, s29, s28
	s_add_i32 s28, s28, s30
	s_add_i32 s30, s28, s31
	s_and_saveexec_b64 s[24:25], s[8:9]
	global_store_dword v30, v59, s[98:99] offset:64 sc1
	v_mov_b32_e32 v70, s30
	global_store_dword v31, v70, s[98:99] offset:64 sc1
	s_mov_b64 exec, s[24:25]
	s_waitcnt vmcnt(23)
; __device__ __forceinline__ void xn2_rows(const bf16* __restrict__ hb, const float* __restrict__ g, bf16* __restrict__ outp, unsigned char* __restrict__ xq, float* __restrict__ xs, int gwave, int nwaves, int lane, int rend) {
;     ...
;         const v4u* xb = (const v4u*)(hb + (size_t)row * D) + lane;
;         float v[2][8]; float ss = 0.f;
; #pragma unroll
;         for (int j = 0; j < 2; ++j) { const v4u w = xb[64 * j]; const unsigned ww[4] = {w.x, w.y, w.z, w.w};
; #pragma unroll
;             for (int e = 0; e < 4; ++e) { v[j][2 * e] = __uint_as_float(ww[e] << 16); v[j][2 * e + 1] = __uint_as_float(ww[e] & 0xffff0000u); ss += v[j][2 * e] * v[j][2 * e] + v[j][2 * e + 1] * v[j][2 * e + 1]; } }
;         ss = wave_sum(ss);
;         const float r = rsqrtf(ss * (1.f / D) + EPS);
;         float y[2][8]; float mx = 0.f;
; #pragma unroll
;         for (int j = 0; j < 2; ++j) { const float4 g0 = ((const float4*)g)[2 * lane + 128 * j], g1 = ((const float4*)g)[2 * lane + 128 * j + 1]; const float gg[8] = {g0.x, g0.y, g0.z, g0.w, g1.x, g1.y, g1.z, g1.w};
; #pragma unroll
;             for (int e = 0; e < 8; ++e) { y[j][e] = v[j][e] * r * gg[e]; mx = fmaxf(mx, fabsf(y[j][e])); }
;             v4u ow; ow.x = pk2(y[j][0], y[j][1]); ow.y = pk2(y[j][2], y[j][3]); ow.z = pk2(y[j][4], y[j][5]); ow.w = pk2(y[j][6], y[j][7]);
;             __builtin_amdgcn_raw_buffer_store_b128(ow, rsO, (int)(((unsigned)row * D + 8u * (unsigned)lane + 512u * j) * 2u), 0, 16); }
;         mx = wave_max_dpp(mx);
;         const float sc = mx > 0.f ? mx * (1.f / 119.f) : 1.f, inv = 1.f / sc;
;         int sx = 0; unsigned W[4];
; #pragma unroll
;         for (int j = 0; j < 2; ++j) { unsigned wh = 0u, wl = 0u;
; #pragma unroll
;             for (int e = 0; e < 8; ++e) { const int q = (int)rintf(y[j][e] * inv); sx += q; const unsigned tq = (unsigned)(q + 8);
;                 wl |= ((tq & 15u) ^ 8u) << (4 * e); wh |= (((unsigned)((int)tq >> 4)) & 15u) << (4 * e); }
;             W[j] = wh; W[2 + j] = wl; }
	v_lshlrev_b32_e32 v34, 16, v108
	v_and_b32_e32 v35, 0xffff0000, v108
	v_lshlrev_b32_e32 v36, 16, v109
	v_and_b32_e32 v37, 0xffff0000, v109
	v_lshlrev_b32_e32 v38, 16, v110
	v_and_b32_e32 v39, 0xffff0000, v110
	v_lshlrev_b32_e32 v40, 16, v111
	v_and_b32_e32 v41, 0xffff0000, v111
	v_lshlrev_b32_e32 v42, 16, v112
	v_and_b32_e32 v43, 0xffff0000, v112
	v_lshlrev_b32_e32 v44, 16, v113
	v_and_b32_e32 v45, 0xffff0000, v113
	v_lshlrev_b32_e32 v46, 16, v114
	v_and_b32_e32 v47, 0xffff0000, v114
	v_lshlrev_b32_e32 v48, 16, v115
	v_and_b32_e32 v49, 0xffff0000, v115
	v_pk_mul_f32 v[50:51], v[34:35], v[34:35]
	v_pk_fma_f32 v[50:51], v[36:37], v[36:37], v[50:51]
	v_pk_fma_f32 v[50:51], v[38:39], v[38:39], v[50:51]
	v_pk_fma_f32 v[50:51], v[40:41], v[40:41], v[50:51]
	v_pk_fma_f32 v[50:51], v[42:43], v[42:43], v[50:51]
	v_pk_fma_f32 v[50:51], v[44:45], v[44:45], v[50:51]
	v_pk_fma_f32 v[50:51], v[46:47], v[46:47], v[50:51]
	v_pk_fma_f32 v[50:51], v[48:49], v[48:49], v[50:51]
	v_add_f32_e32 v52, v50, v51
	s_nop 1
	v_add_f32_dpp v52, v52, v52 quad_perm:[1,0,3,2] row_mask:0xf bank_mask:0xf bound_ctrl:1
	s_nop 1
	v_add_f32_dpp v52, v52, v52 quad_perm:[2,3,0,1] row_mask:0xf bank_mask:0xf bound_ctrl:1
	s_nop 1
	v_add_f32_dpp v52, v52, v52 row_half_mirror row_mask:0xf bank_mask:0xf bound_ctrl:1
	s_nop 1
	v_add_f32_dpp v52, v52, v52 row_mirror row_mask:0xf bank_mask:0xf bound_ctrl:1
	s_nop 1
	v_readlane_b32 s28, v52, 16
	v_readlane_b32 s29, v52, 48
	v_readlane_b32 s24, v52, 0
	v_readlane_b32 s25, v52, 32
	s_nop 1
	v_mov_b32_e32 v52, s28
	v_mov_b32_e32 v53, s29
	v_pk_add_f32 v[52:53], s[24:25], v[52:53]
	s_nop 0
	v_add_f32_e32 v52, v52, v53
	v_fmamk_f32 v52, v52, 0x3a800000, v29
	v_rsq_f32_e32 v54, v52
	s_nop 0
	v_pk_mul_f32 v[56:57], v[54:55], v[34:35] op_sel_hi:[0,1]
	v_pk_mul_f32 v[164:165], v[6:7], v[56:57]
	v_pk_mul_f32 v[56:57], v[54:55], v[36:37] op_sel_hi:[0,1]
	v_pk_mul_f32 v[166:167], v[8:9], v[56:57]
	v_pk_mul_f32 v[56:57], v[54:55], v[38:39] op_sel_hi:[0,1]
	v_pk_mul_f32 v[168:169], v[2:3], v[56:57]
	v_pk_mul_f32 v[56:57], v[54:55], v[40:41] op_sel_hi:[0,1]
	v_pk_mul_f32 v[170:171], v[4:5], v[56:57]
	v_pk_mul_f32 v[56:57], v[54:55], v[42:43] op_sel_hi:[0,1]
	v_pk_mul_f32 v[172:173], v[14:15], v[56:57]
	v_pk_mul_f32 v[56:57], v[54:55], v[44:45] op_sel_hi:[0,1]
	v_pk_mul_f32 v[174:175], v[16:17], v[56:57]
	v_pk_mul_f32 v[56:57], v[54:55], v[46:47] op_sel_hi:[0,1]
	v_pk_mul_f32 v[176:177], v[10:11], v[56:57]
	v_pk_mul_f32 v[56:57], v[54:55], v[48:49] op_sel_hi:[0,1]
	v_pk_mul_f32 v[178:179], v[12:13], v[56:57]
	v_max3_f32 v58, |v164|, 0, |v165|
	v_max3_f32 v58, v58, |v166|, |v167|
	v_max3_f32 v58, v58, |v168|, |v169|
	v_max3_f32 v58, v58, |v170|, |v171|
	v_max3_f32 v58, v58, |v172|, |v173|
	v_max3_f32 v58, v58, |v174|, |v175|
	v_max3_f32 v58, v58, |v176|, |v177|
	v_max3_f32 v58, v58, |v178|, |v179|
	v_cvt_pk_bf16_f32 v62, v164, v165
	v_cvt_pk_bf16_f32 v63, v166, v167
	v_cvt_pk_bf16_f32 v64, v168, v169
	v_cvt_pk_bf16_f32 v65, v170, v171
	v_cvt_pk_bf16_f32 v66, v172, v173
	v_cvt_pk_bf16_f32 v67, v174, v175
	v_cvt_pk_bf16_f32 v68, v176, v177
	v_cvt_pk_bf16_f32 v69, v178, v179
	v_add_u32_e32 v209, 0xc000, v26
	buffer_store_dwordx4 v[62:65], v209, s[12:15], 0 offen sc1
	buffer_store_dwordx4 v[66:69], v209, s[12:15], 0 offen offset:1024 sc1
	s_nop 1
	v_max_f32_dpp v58, v58, v58 quad_perm:[1,0,3,2] row_mask:0xf bank_mask:0xf
	s_nop 1
	v_max_f32_dpp v58, v58, v58 quad_perm:[2,3,0,1] row_mask:0xf bank_mask:0xf
	s_nop 1
	v_max_f32_dpp v58, v58, v58 row_half_mirror row_mask:0xf bank_mask:0xf
	s_nop 1
	v_max_f32_dpp v58, v58, v58 row_mirror row_mask:0xf bank_mask:0xf
	s_nop 1
	v_readlane_b32 s28, v58, 32
	v_readlane_b32 s29, v58, 48
	v_readlane_b32 s24, v58, 0
	v_readlane_b32 s25, v58, 16
	s_nop 1
	v_mov_b32_e32 v59, s29
	v_max_f32_e32 v59, s28, v59
	v_mov_b32_e32 v70, s25
	v_max3_f32 v59, s24, v70, v59
	v_mul_f32_e32 v70, 0x3c09ae41, v59
	v_cmp_lt_f32_e32 vcc, 0, v59
	s_nop 1
	v_cndmask_b32_e32 v59, 1.0, v70, vcc
	v_div_scale_f32 v70, s[24:25], v59, v59, 1.0
	v_rcp_f32_e32 v71, v70
	v_div_scale_f32 v72, vcc, 1.0, v59, 1.0
	v_fma_f32 v73, -v70, v71, 1.0
	v_fmac_f32_e32 v71, v73, v71
	v_mul_f32_e32 v73, v72, v71
	v_fma_f32 v74, -v70, v73, v72
	v_fmac_f32_e32 v73, v74, v71
	v_fma_f32 v70, -v70, v73, v72
	v_div_fmas_f32 v70, v70, v71, v73
	v_div_fixup_f32 v60, v70, v59, 1.0
	v_pk_mul_f32 v[56:57], v[60:61], v[164:165] op_sel_hi:[0,1]
	v_pk_add_f32 v[180:181], s[46:47], v[56:57]
	v_pk_mul_f32 v[56:57], v[60:61], v[166:167] op_sel_hi:[0,1]
	v_pk_add_f32 v[182:183], s[46:47], v[56:57]
	v_pk_mul_f32 v[56:57], v[60:61], v[168:169] op_sel_hi:[0,1]
	v_pk_add_f32 v[184:185], s[46:47], v[56:57]
	v_pk_mul_f32 v[56:57], v[60:61], v[170:171] op_sel_hi:[0,1]
	v_pk_add_f32 v[186:187], s[46:47], v[56:57]
	v_pk_mul_f32 v[56:57], v[60:61], v[172:173] op_sel_hi:[0,1]
	v_pk_add_f32 v[188:189], s[46:47], v[56:57]
	v_pk_mul_f32 v[56:57], v[60:61], v[174:175] op_sel_hi:[0,1]
	v_pk_add_f32 v[190:191], s[46:47], v[56:57]
	v_pk_mul_f32 v[56:57], v[60:61], v[176:177] op_sel_hi:[0,1]
	v_pk_add_f32 v[192:193], s[46:47], v[56:57]
	v_pk_mul_f32 v[56:57], v[60:61], v[178:179] op_sel_hi:[0,1]
	v_pk_add_f32 v[194:195], s[46:47], v[56:57]
	v_add3_u32 v208, v180, v181, v182
	v_add3_u32 v208, v208, v183, v184
	v_add3_u32 v208, v208, v185, v186
	v_add3_u32 v208, v208, v187, v188
	v_add3_u32 v208, v208, v189, v190
	v_add3_u32 v208, v208, v191, v192
	v_add3_u32 v208, v208, v193, v194
	v_add_u32_e32 v208, v208, v195
	v_add_u32_e32 v208, 0x4bffff80, v208
	v_perm_b32 v204, v182, v180, s48
	v_perm_b32 v205, v186, v184, s48
	v_perm_b32 v196, v205, v204, s49
	v_perm_b32 v204, v183, v181, s48
; __device__ __forceinline__ void xn2_rows(const bf16* __restrict__ hb, const float* __restrict__ g, bf16* __restrict__ outp, unsigned char* __restrict__ xq, float* __restrict__ xs, int gwave, int nwaves, int lane, int rend) {
;     ...
;         const v4u* xb = (const v4u*)(hb + (size_t)row * D) + lane;
;         float v[2][8]; float ss = 0.f;
; #pragma unroll
;         for (int j = 0; j < 2; ++j) { const v4u w = xb[64 * j]; const unsigned ww[4] = {w.x, w.y, w.z, w.w};
; #pragma unroll
;             for (int e = 0; e < 4; ++e) { v[j][2 * e] = __uint_as_float(ww[e] << 16); v[j][2 * e + 1] = __uint_as_float(ww[e] & 0xffff0000u); ss += v[j][2 * e] * v[j][2 * e] + v[j][2 * e + 1] * v[j][2 * e + 1]; } }
;         ss = wave_sum(ss);
;         const float r = rsqrtf(ss * (1.f / D) + EPS);
;         float y[2][8]; float mx = 0.f;
; #pragma unroll
;         for (int j = 0; j < 2; ++j) { const float4 g0 = ((const float4*)g)[2 * lane + 128 * j], g1 = ((const float4*)g)[2 * lane + 128 * j + 1]; const float gg[8] = {g0.x, g0.y, g0.z, g0.w, g1.x, g1.y, g1.z, g1.w};
; #pragma unroll
;             for (int e = 0; e < 8; ++e) { y[j][e] = v[j][e] * r * gg[e]; mx = fmaxf(mx, fabsf(y[j][e])); }
;             v4u ow; ow.x = pk2(y[j][0], y[j][1]); ow.y = pk2(y[j][2], y[j][3]); ow.z = pk2(y[j][4], y[j][5]); ow.w = pk2(y[j][6], y[j][7]);
;             __builtin_amdgcn_raw_buffer_store_b128(ow, rsO, (int)(((unsigned)row * D + 8u * (unsigned)lane + 512u * j) * 2u), 0, 16); }
;         mx = wave_max_dpp(mx);
;         const float sc = mx > 0.f ? mx * (1.f / 119.f) : 1.f, inv = 1.f / sc;
;         int sx = 0; unsigned W[4];
; #pragma unroll
;         for (int j = 0; j < 2; ++j) { unsigned wh = 0u, wl = 0u;
; #pragma unroll
;             for (int e = 0; e < 8; ++e) { const int q = (int)rintf(y[j][e] * inv); sx += q; const unsigned tq = (unsigned)(q + 8);
;                 wl |= ((tq & 15u) ^ 8u) << (4 * e); wh |= (((unsigned)((int)tq >> 4)) & 15u) << (4 * e); }
;             W[j] = wh; W[2 + j] = wl; }
;         { const bool o1 = (lane & 1) != 0, o2 = (lane & 2) != 0;
; #pragma unroll
;           for (int p = 0; p < 4; p += 2) { const unsigned t = o1 ? W[p] : W[p + 1]; const unsigned rc = (unsigned)__builtin_amdgcn_update_dpp(0, (int)t, 0xB1, 0xf, 0xf, false); if (o1) W[p] = rc; else W[p + 1] = rc; }
; #pragma unroll
	v_perm_b32 v205, v187, v185, s48
	v_perm_b32 v197, v205, v204, s49
	v_lshlrev_b32_e32 v204, 4, v197
	v_lshrrev_b32_e32 v205, 4, v196
	v_bfi_b32 v202, s45, v196, v204
	v_bfi_b32 v200, s45, v205, v197
	v_xor_b32_e32 v202, 0x88888888, v202
	v_perm_b32 v204, v190, v188, s48
	v_perm_b32 v205, v194, v192, s48
	v_perm_b32 v196, v205, v204, s49
	v_perm_b32 v204, v191, v189, s48
	v_perm_b32 v205, v195, v193, s48
	v_perm_b32 v197, v205, v204, s49
	v_lshlrev_b32_e32 v204, 4, v197
	v_lshrrev_b32_e32 v205, 4, v196
	v_bfi_b32 v203, s45, v196, v204
	v_bfi_b32 v201, s45, v205, v197
	v_xor_b32_e32 v203, 0x88888888, v203
	v_cndmask_b32_e64 v204, v200, v201, s[4:5]
	v_cndmask_b32_e64 v205, v202, v203, s[4:5]
	s_nop 1
	v_mov_b32_dpp v206, v204 quad_perm:[1,0,3,2] row_mask:0xf bank_mask:0xf
	v_mov_b32_dpp v207, v205 quad_perm:[1,0,3,2] row_mask:0xf bank_mask:0xf
	s_nop 0
	v_cndmask_b32_e64 v200, v206, v200, s[4:5]
	v_cndmask_b32_e64 v201, v201, v206, s[4:5]
	v_cndmask_b32_e64 v202, v207, v202, s[4:5]
	v_cndmask_b32_e64 v203, v203, v207, s[4:5]
	v_cndmask_b32_e64 v204, v200, v202, s[6:7]
	v_cndmask_b32_e64 v205, v201, v203, s[6:7]
	s_nop 1
	v_mov_b32_dpp v206, v204 quad_perm:[2,3,0,1] row_mask:0xf bank_mask:0xf
	v_mov_b32_dpp v207, v205 quad_perm:[2,3,0,1] row_mask:0xf bank_mask:0xf
	s_nop 0
	v_cndmask_b32_e64 v200, v206, v200, s[6:7]
	v_cndmask_b32_e64 v202, v202, v206, s[6:7]
	v_cndmask_b32_e64 v201, v207, v201, s[6:7]
	v_cndmask_b32_e64 v203, v203, v207, s[6:7]
	v_add_u32_e32 v209, 0x3000, v33
	buffer_store_dwordx4 v[200:203], v209, s[16:19], 0 offen sc1
	s_nop 1
	v_add_u32_dpp v208, v208, v208 quad_perm:[1,0,3,2] row_mask:0xf bank_mask:0xf bound_ctrl:1
	s_nop 1
	v_add_u32_dpp v208, v208, v208 quad_perm:[2,3,0,1] row_mask:0xf bank_mask:0xf bound_ctrl:1
	s_nop 1
	v_add_u32_dpp v208, v208, v208 row_half_mirror row_mask:0xf bank_mask:0xf bound_ctrl:1
	s_nop 1
	v_add_u32_dpp v208, v208, v208 row_mirror row_mask:0xf bank_mask:0xf bound_ctrl:1
	s_nop 1
	v_readlane_b32 s28, v208, 0
	v_readlane_b32 s29, v208, 16
	v_readlane_b32 s30, v208, 32
	v_readlane_b32 s31, v208, 48
	s_nop 1
	s_add_i32 s28, s29, s28
	s_add_i32 s28, s28, s30
	s_add_i32 s30, s28, s31
	s_and_saveexec_b64 s[24:25], s[8:9]
	global_store_dword v30, v59, s[98:99] offset:96 sc1
	v_mov_b32_e32 v70, s30
	global_store_dword v31, v70, s[98:99] offset:96 sc1
	s_mov_b64 exec, s[24:25]
	s_waitcnt vmcnt(26)
	v_lshlrev_b32_e32 v34, 16, v116
	v_and_b32_e32 v35, 0xffff0000, v116
	v_lshlrev_b32_e32 v36, 16, v117
	v_and_b32_e32 v37, 0xffff0000, v117
	v_lshlrev_b32_e32 v38, 16, v118
	v_and_b32_e32 v39, 0xffff0000, v118
	v_lshlrev_b32_e32 v40, 16, v119
	v_and_b32_e32 v41, 0xffff0000, v119
	v_lshlrev_b32_e32 v42, 16, v120
	v_and_b32_e32 v43, 0xffff0000, v120
	v_lshlrev_b32_e32 v44, 16, v121
	v_and_b32_e32 v45, 0xffff0000, v121
	v_lshlrev_b32_e32 v46, 16, v122
	v_and_b32_e32 v47, 0xffff0000, v122
	v_lshlrev_b32_e32 v48, 16, v123
	v_and_b32_e32 v49, 0xffff0000, v123
	v_pk_mul_f32 v[50:51], v[34:35], v[34:35]
	v_pk_fma_f32 v[50:51], v[36:37], v[36:37], v[50:51]
	v_pk_fma_f32 v[50:51], v[38:39], v[38:39], v[50:51]
	v_pk_fma_f32 v[50:51], v[40:41], v[40:41], v[50:51]
	v_pk_fma_f32 v[50:51], v[42:43], v[42:43], v[50:51]
	v_pk_fma_f32 v[50:51], v[44:45], v[44:45], v[50:51]
	v_pk_fma_f32 v[50:51], v[46:47], v[46:47], v[50:51]
	v_pk_fma_f32 v[50:51], v[48:49], v[48:49], v[50:51]
	v_add_f32_e32 v52, v50, v51
	s_nop 1
	v_add_f32_dpp v52, v52, v52 quad_perm:[1,0,3,2] row_mask:0xf bank_mask:0xf bound_ctrl:1
	s_nop 1
	v_add_f32_dpp v52, v52, v52 quad_perm:[2,3,0,1] row_mask:0xf bank_mask:0xf bound_ctrl:1
	s_nop 1
	v_add_f32_dpp v52, v52, v52 row_half_mirror row_mask:0xf bank_mask:0xf bound_ctrl:1
	s_nop 1
	v_add_f32_dpp v52, v52, v52 row_mirror row_mask:0xf bank_mask:0xf bound_ctrl:1
	s_nop 1
	v_readlane_b32 s28, v52, 16
	v_readlane_b32 s29, v52, 48
	v_readlane_b32 s24, v52, 0
	v_readlane_b32 s25, v52, 32
	s_nop 1
	v_mov_b32_e32 v52, s28
	v_mov_b32_e32 v53, s29
	v_pk_add_f32 v[52:53], s[24:25], v[52:53]
	s_nop 0
	v_add_f32_e32 v52, v52, v53
	v_fmamk_f32 v52, v52, 0x3a800000, v29
	v_rsq_f32_e32 v54, v52
	s_nop 0
	v_pk_mul_f32 v[56:57], v[54:55], v[34:35] op_sel_hi:[0,1]
	v_pk_mul_f32 v[164:165], v[6:7], v[56:57]
	v_pk_mul_f32 v[56:57], v[54:55], v[36:37] op_sel_hi:[0,1]
	v_pk_mul_f32 v[166:167], v[8:9], v[56:57]
	v_pk_mul_f32 v[56:57], v[54:55], v[38:39] op_sel_hi:[0,1]
	v_pk_mul_f32 v[168:169], v[2:3], v[56:57]
	v_pk_mul_f32 v[56:57], v[54:55], v[40:41] op_sel_hi:[0,1]
	v_pk_mul_f32 v[170:171], v[4:5], v[56:57]
	v_pk_mul_f32 v[56:57], v[54:55], v[42:43] op_sel_hi:[0,1]
	v_pk_mul_f32 v[172:173], v[14:15], v[56:57]
	v_pk_mul_f32 v[56:57], v[54:55], v[44:45] op_sel_hi:[0,1]
	v_pk_mul_f32 v[174:175], v[16:17], v[56:57]
	v_pk_mul_f32 v[56:57], v[54:55], v[46:47] op_sel_hi:[0,1]
	v_pk_mul_f32 v[176:177], v[10:11], v[56:57]
	v_pk_mul_f32 v[56:57], v[54:55], v[48:49] op_sel_hi:[0,1]
	v_pk_mul_f32 v[178:179], v[12:13], v[56:57]
	v_max3_f32 v58, |v164|, 0, |v165|
	v_max3_f32 v58, v58, |v166|, |v167|
	v_max3_f32 v58, v58, |v168|, |v169|
	v_max3_f32 v58, v58, |v170|, |v171|
	v_max3_f32 v58, v58, |v172|, |v173|
	v_max3_f32 v58, v58, |v174|, |v175|
	v_max3_f32 v58, v58, |v176|, |v177|
	v_max3_f32 v58, v58, |v178|, |v179|
	v_cvt_pk_bf16_f32 v62, v164, v165
	v_cvt_pk_bf16_f32 v63, v166, v167
	v_cvt_pk_bf16_f32 v64, v168, v169
	v_cvt_pk_bf16_f32 v65, v170, v171
	v_cvt_pk_bf16_f32 v66, v172, v173
	v_cvt_pk_bf16_f32 v67, v174, v175
	v_cvt_pk_bf16_f32 v68, v176, v177
	v_cvt_pk_bf16_f32 v69, v178, v179
	v_add_u32_e32 v209, 0x10000, v26
	buffer_store_dwordx4 v[62:65], v209, s[12:15], 0 offen sc1
	buffer_store_dwordx4 v[66:69], v209, s[12:15], 0 offen offset:1024 sc1
; __device__ __forceinline__ void xn2_rows(const bf16* __restrict__ hb, const float* __restrict__ g, bf16* __restrict__ outp, unsigned char* __restrict__ xq, float* __restrict__ xs, int gwave, int nwaves, int lane, int rend) {
;     ...
;         mx = wave_max_dpp(mx);
;         const float sc = mx > 0.f ? mx * (1.f / 119.f) : 1.f, inv = 1.f / sc;
;         int sx = 0; unsigned W[4];
; #pragma unroll
;         for (int j = 0; j < 2; ++j) { unsigned wh = 0u, wl = 0u;
; #pragma unroll
;             for (int e = 0; e < 8; ++e) { const int q = (int)rintf(y[j][e] * inv); sx += q; const unsigned tq = (unsigned)(q + 8);
;                 wl |= ((tq & 15u) ^ 8u) << (4 * e); wh |= (((unsigned)((int)tq >> 4)) & 15u) << (4 * e); }
;             W[j] = wh; W[2 + j] = wl; }
;         { const bool o1 = (lane & 1) != 0, o2 = (lane & 2) != 0;
; #pragma unroll
;           for (int p = 0; p < 4; p += 2) { const unsigned t = o1 ? W[p] : W[p + 1]; const unsigned rc = (unsigned)__builtin_amdgcn_update_dpp(0, (int)t, 0xB1, 0xf, 0xf, false); if (o1) W[p] = rc; else W[p + 1] = rc; }
; #pragma unroll
;           for (int p = 0; p < 2; ++p) { const unsigned t = o2 ? W[p] : W[p + 2]; const unsigned rc = (unsigned)__builtin_amdgcn_update_dpp(0, (int)t, 0x4E, 0xf, 0xf, false); if (o2) W[p] = rc; else W[p + 2] = rc; } }
;         { const int m = lane & 3; v4u pw; pw.x = W[0]; pw.y = W[1]; pw.z = W[2]; pw.w = W[3];
;           __builtin_amdgcn_raw_buffer_store_b128(pw, rsQ, (int)((m & 2 ? 8u * (unsigned)MiB : 0u) + (unsigned)row * 512u + (unsigned)(m & 1) * 256u + 16u * (unsigned)(lane >> 2)), 0, 16); }
;         sx = wave_sum_dpp_i(sx);
;         if (lane == 0) { __hip_atomic_store(xs + row, sc, __ATOMIC_RELAXED, __HIP_MEMORY_SCOPE_AGENT); __hip_atomic_store((int*)(xs + T) + row, sx, __ATOMIC_RELAXED, __HIP_MEMORY_SCOPE_AGENT); }
	s_nop 1
	v_max_f32_dpp v58, v58, v58 quad_perm:[1,0,3,2] row_mask:0xf bank_mask:0xf
	s_nop 1
	v_max_f32_dpp v58, v58, v58 quad_perm:[2,3,0,1] row_mask:0xf bank_mask:0xf
	s_nop 1
	v_max_f32_dpp v58, v58, v58 row_half_mirror row_mask:0xf bank_mask:0xf
	s_nop 1
	v_max_f32_dpp v58, v58, v58 row_mirror row_mask:0xf bank_mask:0xf
	s_nop 1
	v_readlane_b32 s28, v58, 32
	v_readlane_b32 s29, v58, 48
	v_readlane_b32 s24, v58, 0
	v_readlane_b32 s25, v58, 16
	s_nop 1
	v_mov_b32_e32 v59, s29
	v_max_f32_e32 v59, s28, v59
	v_mov_b32_e32 v70, s25
	v_max3_f32 v59, s24, v70, v59
	v_mul_f32_e32 v70, 0x3c09ae41, v59
	v_cmp_lt_f32_e32 vcc, 0, v59
	s_nop 1
	v_cndmask_b32_e32 v59, 1.0, v70, vcc
	v_div_scale_f32 v70, s[24:25], v59, v59, 1.0
	v_rcp_f32_e32 v71, v70
	v_div_scale_f32 v72, vcc, 1.0, v59, 1.0
	v_fma_f32 v73, -v70, v71, 1.0
	v_fmac_f32_e32 v71, v73, v71
	v_mul_f32_e32 v73, v72, v71
	v_fma_f32 v74, -v70, v73, v72
	v_fmac_f32_e32 v73, v74, v71
	v_fma_f32 v70, -v70, v73, v72
	v_div_fmas_f32 v70, v70, v71, v73
	v_div_fixup_f32 v60, v70, v59, 1.0
	v_pk_mul_f32 v[56:57], v[60:61], v[164:165] op_sel_hi:[0,1]
	v_pk_add_f32 v[180:181], s[46:47], v[56:57]
	v_pk_mul_f32 v[56:57], v[60:61], v[166:167] op_sel_hi:[0,1]
	v_pk_add_f32 v[182:183], s[46:47], v[56:57]
	v_pk_mul_f32 v[56:57], v[60:61], v[168:169] op_sel_hi:[0,1]
	v_pk_add_f32 v[184:185], s[46:47], v[56:57]
	v_pk_mul_f32 v[56:57], v[60:61], v[170:171] op_sel_hi:[0,1]
	v_pk_add_f32 v[186:187], s[46:47], v[56:57]
	v_pk_mul_f32 v[56:57], v[60:61], v[172:173] op_sel_hi:[0,1]
	v_pk_add_f32 v[188:189], s[46:47], v[56:57]
	v_pk_mul_f32 v[56:57], v[60:61], v[174:175] op_sel_hi:[0,1]
	v_pk_add_f32 v[190:191], s[46:47], v[56:57]
	v_pk_mul_f32 v[56:57], v[60:61], v[176:177] op_sel_hi:[0,1]
	v_pk_add_f32 v[192:193], s[46:47], v[56:57]
	v_pk_mul_f32 v[56:57], v[60:61], v[178:179] op_sel_hi:[0,1]
	v_pk_add_f32 v[194:195], s[46:47], v[56:57]
	v_add3_u32 v208, v180, v181, v182
	v_add3_u32 v208, v208, v183, v184
	v_add3_u32 v208, v208, v185, v186
	v_add3_u32 v208, v208, v187, v188
	v_add3_u32 v208, v208, v189, v190
	v_add3_u32 v208, v208, v191, v192
	v_add3_u32 v208, v208, v193, v194
	v_add_u32_e32 v208, v208, v195
	v_add_u32_e32 v208, 0x4bffff80, v208
	v_perm_b32 v204, v182, v180, s48
	v_perm_b32 v205, v186, v184, s48
	v_perm_b32 v196, v205, v204, s49
	v_perm_b32 v204, v183, v181, s48
	v_perm_b32 v205, v187, v185, s48
	v_perm_b32 v197, v205, v204, s49
	v_lshlrev_b32_e32 v204, 4, v197
	v_lshrrev_b32_e32 v205, 4, v196
	v_bfi_b32 v202, s45, v196, v204
	v_bfi_b32 v200, s45, v205, v197
	v_xor_b32_e32 v202, 0x88888888, v202
	v_perm_b32 v204, v190, v188, s48
	v_perm_b32 v205, v194, v192, s48
	v_perm_b32 v196, v205, v204, s49
	v_perm_b32 v204, v191, v189, s48
	v_perm_b32 v205, v195, v193, s48
	v_perm_b32 v197, v205, v204, s49
	v_lshlrev_b32_e32 v204, 4, v197
	v_lshrrev_b32_e32 v205, 4, v196
	v_bfi_b32 v203, s45, v196, v204
	v_bfi_b32 v201, s45, v205, v197
	v_xor_b32_e32 v203, 0x88888888, v203
	v_cndmask_b32_e64 v204, v200, v201, s[4:5]
	v_cndmask_b32_e64 v205, v202, v203, s[4:5]
	s_nop 1
	v_mov_b32_dpp v206, v204 quad_perm:[1,0,3,2] row_mask:0xf bank_mask:0xf
	v_mov_b32_dpp v207, v205 quad_perm:[1,0,3,2] row_mask:0xf bank_mask:0xf
	s_nop 0
	v_cndmask_b32_e64 v200, v206, v200, s[4:5]
	v_cndmask_b32_e64 v201, v201, v206, s[4:5]
	v_cndmask_b32_e64 v202, v207, v202, s[4:5]
	v_cndmask_b32_e64 v203, v203, v207, s[4:5]
	v_cndmask_b32_e64 v204, v200, v202, s[6:7]
	v_cndmask_b32_e64 v205, v201, v203, s[6:7]
	s_nop 1
	v_mov_b32_dpp v206, v204 quad_perm:[2,3,0,1] row_mask:0xf bank_mask:0xf
	v_mov_b32_dpp v207, v205 quad_perm:[2,3,0,1] row_mask:0xf bank_mask:0xf
	s_nop 0
	v_cndmask_b32_e64 v200, v206, v200, s[6:7]
	v_cndmask_b32_e64 v202, v202, v206, s[6:7]
	v_cndmask_b32_e64 v201, v207, v201, s[6:7]
	v_cndmask_b32_e64 v203, v203, v207, s[6:7]
	v_add_u32_e32 v209, 0x4000, v33
	buffer_store_dwordx4 v[200:203], v209, s[16:19], 0 offen sc1
	s_nop 1
	v_add_u32_dpp v208, v208, v208 quad_perm:[1,0,3,2] row_mask:0xf bank_mask:0xf bound_ctrl:1
	s_nop 1
	v_add_u32_dpp v208, v208, v208 quad_perm:[2,3,0,1] row_mask:0xf bank_mask:0xf bound_ctrl:1
	s_nop 1
	v_add_u32_dpp v208, v208, v208 row_half_mirror row_mask:0xf bank_mask:0xf bound_ctrl:1
	s_nop 1
	v_add_u32_dpp v208, v208, v208 row_mirror row_mask:0xf bank_mask:0xf bound_ctrl:1
	s_nop 1
	v_readlane_b32 s28, v208, 0
	v_readlane_b32 s29, v208, 16
	v_readlane_b32 s30, v208, 32
	v_readlane_b32 s31, v208, 48
	s_nop 1
	s_add_i32 s28, s29, s28
	s_add_i32 s28, s28, s30
	s_add_i32 s30, s28, s31
	s_and_saveexec_b64 s[24:25], s[8:9]
	global_store_dword v30, v59, s[98:99] offset:128 sc1
	v_mov_b32_e32 v70, s30
	global_store_dword v31, v70, s[98:99] offset:128 sc1
	s_mov_b64 exec, s[24:25]
	s_waitcnt vmcnt(29)
; __device__ __forceinline__ void xn2_rows(const bf16* __restrict__ hb, const float* __restrict__ g, bf16* __restrict__ outp, unsigned char* __restrict__ xq, float* __restrict__ xs, int gwave, int nwaves, int lane, int rend) {
;     ...
;         const v4u* xb = (const v4u*)(hb + (size_t)row * D) + lane;
;         float v[2][8]; float ss = 0.f;
; #pragma unroll
;         for (int j = 0; j < 2; ++j) { const v4u w = xb[64 * j]; const unsigned ww[4] = {w.x, w.y, w.z, w.w};
; #pragma unroll
;             for (int e = 0; e < 4; ++e) { v[j][2 * e] = __uint_as_float(ww[e] << 16); v[j][2 * e + 1] = __uint_as_float(ww[e] & 0xffff0000u); ss += v[j][2 * e] * v[j][2 * e] + v[j][2 * e + 1] * v[j][2 * e + 1]; } }
;         ss = wave_sum(ss);
;         const float r = rsqrtf(ss * (1.f / D) + EPS);
;         float y[2][8]; float mx = 0.f;
; #pragma unroll
;         for (int j = 0; j < 2; ++j) { const float4 g0 = ((const float4*)g)[2 * lane + 128 * j], g1 = ((const float4*)g)[2 * lane + 128 * j + 1]; const float gg[8] = {g0.x, g0.y, g0.z, g0.w, g1.x, g1.y, g1.z, g1.w};
; #pragma unroll
;             for (int e = 0; e < 8; ++e) { y[j][e] = v[j][e] * r * gg[e]; mx = fmaxf(mx, fabsf(y[j][e])); }
;             v4u ow; ow.x = pk2(y[j][0], y[j][1]); ow.y = pk2(y[j][2], y[j][3]); ow.z = pk2(y[j][4], y[j][5]); ow.w = pk2(y[j][6], y[j][7]);
;             __builtin_amdgcn_raw_buffer_store_b128(ow, rsO, (int)(((unsigned)row * D + 8u * (unsigned)lane + 512u * j) * 2u), 0, 16); }
;         mx = wave_max_dpp(mx);
;         const float sc = mx > 0.f ? mx * (1.f / 119.f) : 1.f, inv = 1.f / sc;
;         int sx = 0; unsigned W[4];
; #pragma unroll
;         for (int j = 0; j < 2; ++j) { unsigned wh = 0u, wl = 0u;
; #pragma unroll
;             for (int e = 0; e < 8; ++e) { const int q = (int)rintf(y[j][e] * inv); sx += q; const unsigned tq = (unsigned)(q + 8);
;                 wl |= ((tq & 15u) ^ 8u) << (4 * e); wh |= (((unsigned)((int)tq >> 4)) & 15u) << (4 * e); }
;             W[j] = wh; W[2 + j] = wl; }
	v_lshlrev_b32_e32 v34, 16, v124
	v_and_b32_e32 v35, 0xffff0000, v124
	v_lshlrev_b32_e32 v36, 16, v125
	v_and_b32_e32 v37, 0xffff0000, v125
	v_lshlrev_b32_e32 v38, 16, v126
	v_and_b32_e32 v39, 0xffff0000, v126
	v_lshlrev_b32_e32 v40, 16, v127
	v_and_b32_e32 v41, 0xffff0000, v127
	v_lshlrev_b32_e32 v42, 16, v128
	v_and_b32_e32 v43, 0xffff0000, v128
	v_lshlrev_b32_e32 v44, 16, v129
	v_and_b32_e32 v45, 0xffff0000, v129
	v_lshlrev_b32_e32 v46, 16, v130
	v_and_b32_e32 v47, 0xffff0000, v130
	v_lshlrev_b32_e32 v48, 16, v131
	v_and_b32_e32 v49, 0xffff0000, v131
	v_pk_mul_f32 v[50:51], v[34:35], v[34:35]
	v_pk_fma_f32 v[50:51], v[36:37], v[36:37], v[50:51]
	v_pk_fma_f32 v[50:51], v[38:39], v[38:39], v[50:51]
	v_pk_fma_f32 v[50:51], v[40:41], v[40:41], v[50:51]
	v_pk_fma_f32 v[50:51], v[42:43], v[42:43], v[50:51]
	v_pk_fma_f32 v[50:51], v[44:45], v[44:45], v[50:51]
	v_pk_fma_f32 v[50:51], v[46:47], v[46:47], v[50:51]
	v_pk_fma_f32 v[50:51], v[48:49], v[48:49], v[50:51]
	v_add_f32_e32 v52, v50, v51
	s_nop 1
	v_add_f32_dpp v52, v52, v52 quad_perm:[1,0,3,2] row_mask:0xf bank_mask:0xf bound_ctrl:1
	s_nop 1
	v_add_f32_dpp v52, v52, v52 quad_perm:[2,3,0,1] row_mask:0xf bank_mask:0xf bound_ctrl:1
	s_nop 1
	v_add_f32_dpp v52, v52, v52 row_half_mirror row_mask:0xf bank_mask:0xf bound_ctrl:1
	s_nop 1
	v_add_f32_dpp v52, v52, v52 row_mirror row_mask:0xf bank_mask:0xf bound_ctrl:1
	s_nop 1
	v_readlane_b32 s28, v52, 16
	v_readlane_b32 s29, v52, 48
	v_readlane_b32 s24, v52, 0
	v_readlane_b32 s25, v52, 32
	s_nop 1
	v_mov_b32_e32 v52, s28
	v_mov_b32_e32 v53, s29
	v_pk_add_f32 v[52:53], s[24:25], v[52:53]
	s_nop 0
	v_add_f32_e32 v52, v52, v53
	v_fmamk_f32 v52, v52, 0x3a800000, v29
	v_rsq_f32_e32 v54, v52
	s_nop 0
	v_pk_mul_f32 v[56:57], v[54:55], v[34:35] op_sel_hi:[0,1]
	v_pk_mul_f32 v[164:165], v[6:7], v[56:57]
	v_pk_mul_f32 v[56:57], v[54:55], v[36:37] op_sel_hi:[0,1]
	v_pk_mul_f32 v[166:167], v[8:9], v[56:57]
	v_pk_mul_f32 v[56:57], v[54:55], v[38:39] op_sel_hi:[0,1]
	v_pk_mul_f32 v[168:169], v[2:3], v[56:57]
	v_pk_mul_f32 v[56:57], v[54:55], v[40:41] op_sel_hi:[0,1]
	v_pk_mul_f32 v[170:171], v[4:5], v[56:57]
	v_pk_mul_f32 v[56:57], v[54:55], v[42:43] op_sel_hi:[0,1]
	v_pk_mul_f32 v[172:173], v[14:15], v[56:57]
	v_pk_mul_f32 v[56:57], v[54:55], v[44:45] op_sel_hi:[0,1]
	v_pk_mul_f32 v[174:175], v[16:17], v[56:57]
	v_pk_mul_f32 v[56:57], v[54:55], v[46:47] op_sel_hi:[0,1]
	v_pk_mul_f32 v[176:177], v[10:11], v[56:57]
	v_pk_mul_f32 v[56:57], v[54:55], v[48:49] op_sel_hi:[0,1]
	v_pk_mul_f32 v[178:179], v[12:13], v[56:57]
	v_max3_f32 v58, |v164|, 0, |v165|
	v_max3_f32 v58, v58, |v166|, |v167|
	v_max3_f32 v58, v58, |v168|, |v169|
	v_max3_f32 v58, v58, |v170|, |v171|
	v_max3_f32 v58, v58, |v172|, |v173|
	v_max3_f32 v58, v58, |v174|, |v175|
	v_max3_f32 v58, v58, |v176|, |v177|
	v_max3_f32 v58, v58, |v178|, |v179|
	v_cvt_pk_bf16_f32 v62, v164, v165
	v_cvt_pk_bf16_f32 v63, v166, v167
	v_cvt_pk_bf16_f32 v64, v168, v169
	v_cvt_pk_bf16_f32 v65, v170, v171
	v_cvt_pk_bf16_f32 v66, v172, v173
	v_cvt_pk_bf16_f32 v67, v174, v175
	v_cvt_pk_bf16_f32 v68, v176, v177
	v_cvt_pk_bf16_f32 v69, v178, v179
	v_add_u32_e32 v209, 0x14000, v26
	buffer_store_dwordx4 v[62:65], v209, s[12:15], 0 offen sc1
	buffer_store_dwordx4 v[66:69], v209, s[12:15], 0 offen offset:1024 sc1
	s_nop 1
	v_max_f32_dpp v58, v58, v58 quad_perm:[1,0,3,2] row_mask:0xf bank_mask:0xf
	s_nop 1
	v_max_f32_dpp v58, v58, v58 quad_perm:[2,3,0,1] row_mask:0xf bank_mask:0xf
	s_nop 1
	v_max_f32_dpp v58, v58, v58 row_half_mirror row_mask:0xf bank_mask:0xf
	s_nop 1
	v_max_f32_dpp v58, v58, v58 row_mirror row_mask:0xf bank_mask:0xf
	s_nop 1
	v_readlane_b32 s28, v58, 32
	v_readlane_b32 s29, v58, 48
	v_readlane_b32 s24, v58, 0
	v_readlane_b32 s25, v58, 16
	s_nop 1
	v_mov_b32_e32 v59, s29
	v_max_f32_e32 v59, s28, v59
	v_mov_b32_e32 v70, s25
	v_max3_f32 v59, s24, v70, v59
	v_mul_f32_e32 v70, 0x3c09ae41, v59
	v_cmp_lt_f32_e32 vcc, 0, v59
	s_nop 1
	v_cndmask_b32_e32 v59, 1.0, v70, vcc
	v_div_scale_f32 v70, s[24:25], v59, v59, 1.0
	v_rcp_f32_e32 v71, v70
	v_div_scale_f32 v72, vcc, 1.0, v59, 1.0
	v_fma_f32 v73, -v70, v71, 1.0
	v_fmac_f32_e32 v71, v73, v71
	v_mul_f32_e32 v73, v72, v71
	v_fma_f32 v74, -v70, v73, v72
	v_fmac_f32_e32 v73, v74, v71
	v_fma_f32 v70, -v70, v73, v72
	v_div_fmas_f32 v70, v70, v71, v73
	v_div_fixup_f32 v60, v70, v59, 1.0
	v_pk_mul_f32 v[56:57], v[60:61], v[164:165] op_sel_hi:[0,1]
	v_pk_add_f32 v[180:181], s[46:47], v[56:57]
	v_pk_mul_f32 v[56:57], v[60:61], v[166:167] op_sel_hi:[0,1]
	v_pk_add_f32 v[182:183], s[46:47], v[56:57]
	v_pk_mul_f32 v[56:57], v[60:61], v[168:169] op_sel_hi:[0,1]
	v_pk_add_f32 v[184:185], s[46:47], v[56:57]
	v_pk_mul_f32 v[56:57], v[60:61], v[170:171] op_sel_hi:[0,1]
	v_pk_add_f32 v[186:187], s[46:47], v[56:57]
	v_pk_mul_f32 v[56:57], v[60:61], v[172:173] op_sel_hi:[0,1]
	v_pk_add_f32 v[188:189], s[46:47], v[56:57]
	v_pk_mul_f32 v[56:57], v[60:61], v[174:175] op_sel_hi:[0,1]
	v_pk_add_f32 v[190:191], s[46:47], v[56:57]
	v_pk_mul_f32 v[56:57], v[60:61], v[176:177] op_sel_hi:[0,1]
	v_pk_add_f32 v[192:193], s[46:47], v[56:57]
	v_pk_mul_f32 v[56:57], v[60:61], v[178:179] op_sel_hi:[0,1]
	v_pk_add_f32 v[194:195], s[46:47], v[56:57]
	v_add3_u32 v208, v180, v181, v182
	v_add3_u32 v208, v208, v183, v184
	v_add3_u32 v208, v208, v185, v186
	v_add3_u32 v208, v208, v187, v188
	v_add3_u32 v208, v208, v189, v190
	v_add3_u32 v208, v208, v191, v192
	v_add3_u32 v208, v208, v193, v194
	v_add_u32_e32 v208, v208, v195
	v_add_u32_e32 v208, 0x4bffff80, v208
	v_perm_b32 v204, v182, v180, s48
	v_perm_b32 v205, v186, v184, s48
	v_perm_b32 v196, v205, v204, s49
	v_perm_b32 v204, v183, v181, s48
; __device__ __forceinline__ void xn2_rows(const bf16* __restrict__ hb, const float* __restrict__ g, bf16* __restrict__ outp, unsigned char* __restrict__ xq, float* __restrict__ xs, int gwave, int nwaves, int lane, int rend) {
;     ...
;         const v4u* xb = (const v4u*)(hb + (size_t)row * D) + lane;
;         float v[2][8]; float ss = 0.f;
; #pragma unroll
;         for (int j = 0; j < 2; ++j) { const v4u w = xb[64 * j]; const unsigned ww[4] = {w.x, w.y, w.z, w.w};
; #pragma unroll
;             for (int e = 0; e < 4; ++e) { v[j][2 * e] = __uint_as_float(ww[e] << 16); v[j][2 * e + 1] = __uint_as_float(ww[e] & 0xffff0000u); ss += v[j][2 * e] * v[j][2 * e] + v[j][2 * e + 1] * v[j][2 * e + 1]; } }
;         ss = wave_sum(ss);
;         const float r = rsqrtf(ss * (1.f / D) + EPS);
;         float y[2][8]; float mx = 0.f;
; #pragma unroll
;         for (int j = 0; j < 2; ++j) { const float4 g0 = ((const float4*)g)[2 * lane + 128 * j], g1 = ((const float4*)g)[2 * lane + 128 * j + 1]; const float gg[8] = {g0.x, g0.y, g0.z, g0.w, g1.x, g1.y, g1.z, g1.w};
; #pragma unroll
;             for (int e = 0; e < 8; ++e) { y[j][e] = v[j][e] * r * gg[e]; mx = fmaxf(mx, fabsf(y[j][e])); }
;             v4u ow; ow.x = pk2(y[j][0], y[j][1]); ow.y = pk2(y[j][2], y[j][3]); ow.z = pk2(y[j][4], y[j][5]); ow.w = pk2(y[j][6], y[j][7]);
;             __builtin_amdgcn_raw_buffer_store_b128(ow, rsO, (int)(((unsigned)row * D + 8u * (unsigned)lane + 512u * j) * 2u), 0, 16); }
;         mx = wave_max_dpp(mx);
;         const float sc = mx > 0.f ? mx * (1.f / 119.f) : 1.f, inv = 1.f / sc;
;         int sx = 0; unsigned W[4];
; #pragma unroll
;         for (int j = 0; j < 2; ++j) { unsigned wh = 0u, wl = 0u;
; #pragma unroll
;             for (int e = 0; e < 8; ++e) { const int q = (int)rintf(y[j][e] * inv); sx += q; const unsigned tq = (unsigned)(q + 8);
;                 wl |= ((tq & 15u) ^ 8u) << (4 * e); wh |= (((unsigned)((int)tq >> 4)) & 15u) << (4 * e); }
;             W[j] = wh; W[2 + j] = wl; }
;         { const bool o1 = (lane & 1) != 0, o2 = (lane & 2) != 0;
; #pragma unroll
;           for (int p = 0; p < 4; p += 2) { const unsigned t = o1 ? W[p] : W[p + 1]; const unsigned rc = (unsigned)__builtin_amdgcn_update_dpp(0, (int)t, 0xB1, 0xf, 0xf, false); if (o1) W[p] = rc; else W[p + 1] = rc; }
; #pragma unroll
	v_perm_b32 v205, v187, v185, s48
	v_perm_b32 v197, v205, v204, s49
	v_lshlrev_b32_e32 v204, 4, v197
	v_lshrrev_b32_e32 v205, 4, v196
	v_bfi_b32 v202, s45, v196, v204
	v_bfi_b32 v200, s45, v205, v197
	v_xor_b32_e32 v202, 0x88888888, v202
	v_perm_b32 v204, v190, v188, s48
	v_perm_b32 v205, v194, v192, s48
	v_perm_b32 v196, v205, v204, s49
	v_perm_b32 v204, v191, v189, s48
	v_perm_b32 v205, v195, v193, s48
	v_perm_b32 v197, v205, v204, s49
	v_lshlrev_b32_e32 v204, 4, v197
	v_lshrrev_b32_e32 v205, 4, v196
	v_bfi_b32 v203, s45, v196, v204
	v_bfi_b32 v201, s45, v205, v197
	v_xor_b32_e32 v203, 0x88888888, v203
	v_cndmask_b32_e64 v204, v200, v201, s[4:5]
	v_cndmask_b32_e64 v205, v202, v203, s[4:5]
	s_nop 1
	v_mov_b32_dpp v206, v204 quad_perm:[1,0,3,2] row_mask:0xf bank_mask:0xf
	v_mov_b32_dpp v207, v205 quad_perm:[1,0,3,2] row_mask:0xf bank_mask:0xf
	s_nop 0
	v_cndmask_b32_e64 v200, v206, v200, s[4:5]
	v_cndmask_b32_e64 v201, v201, v206, s[4:5]
	v_cndmask_b32_e64 v202, v207, v202, s[4:5]
	v_cndmask_b32_e64 v203, v203, v207, s[4:5]
	v_cndmask_b32_e64 v204, v200, v202, s[6:7]
	v_cndmask_b32_e64 v205, v201, v203, s[6:7]
	s_nop 1
	v_mov_b32_dpp v206, v204 quad_perm:[2,3,0,1] row_mask:0xf bank_mask:0xf
	v_mov_b32_dpp v207, v205 quad_perm:[2,3,0,1] row_mask:0xf bank_mask:0xf
	s_nop 0
	v_cndmask_b32_e64 v200, v206, v200, s[6:7]
	v_cndmask_b32_e64 v202, v202, v206, s[6:7]
	v_cndmask_b32_e64 v201, v207, v201, s[6:7]
	v_cndmask_b32_e64 v203, v203, v207, s[6:7]
	v_add_u32_e32 v209, 0x5000, v33
	buffer_store_dwordx4 v[200:203], v209, s[16:19], 0 offen sc1
	s_nop 1
	v_add_u32_dpp v208, v208, v208 quad_perm:[1,0,3,2] row_mask:0xf bank_mask:0xf bound_ctrl:1
	s_nop 1
	v_add_u32_dpp v208, v208, v208 quad_perm:[2,3,0,1] row_mask:0xf bank_mask:0xf bound_ctrl:1
	s_nop 1
	v_add_u32_dpp v208, v208, v208 row_half_mirror row_mask:0xf bank_mask:0xf bound_ctrl:1
	s_nop 1
	v_add_u32_dpp v208, v208, v208 row_mirror row_mask:0xf bank_mask:0xf bound_ctrl:1
	s_nop 1
	v_readlane_b32 s28, v208, 0
	v_readlane_b32 s29, v208, 16
	v_readlane_b32 s30, v208, 32
	v_readlane_b32 s31, v208, 48
	s_nop 1
	s_add_i32 s28, s29, s28
	s_add_i32 s28, s28, s30
	s_add_i32 s30, s28, s31
	s_and_saveexec_b64 s[24:25], s[8:9]
	global_store_dword v30, v59, s[98:99] offset:160 sc1
	v_mov_b32_e32 v70, s30
	global_store_dword v31, v70, s[98:99] offset:160 sc1
	s_mov_b64 exec, s[24:25]
	s_waitcnt vmcnt(32)
	v_lshlrev_b32_e32 v34, 16, v132
	v_and_b32_e32 v35, 0xffff0000, v132
	v_lshlrev_b32_e32 v36, 16, v133
	v_and_b32_e32 v37, 0xffff0000, v133
	v_lshlrev_b32_e32 v38, 16, v134
	v_and_b32_e32 v39, 0xffff0000, v134
	v_lshlrev_b32_e32 v40, 16, v135
	v_and_b32_e32 v41, 0xffff0000, v135
	v_lshlrev_b32_e32 v42, 16, v136
	v_and_b32_e32 v43, 0xffff0000, v136
	v_lshlrev_b32_e32 v44, 16, v137
	v_and_b32_e32 v45, 0xffff0000, v137
	v_lshlrev_b32_e32 v46, 16, v138
	v_and_b32_e32 v47, 0xffff0000, v138
	v_lshlrev_b32_e32 v48, 16, v139
	v_and_b32_e32 v49, 0xffff0000, v139
	v_pk_mul_f32 v[50:51], v[34:35], v[34:35]
	v_pk_fma_f32 v[50:51], v[36:37], v[36:37], v[50:51]
	v_pk_fma_f32 v[50:51], v[38:39], v[38:39], v[50:51]
	v_pk_fma_f32 v[50:51], v[40:41], v[40:41], v[50:51]
	v_pk_fma_f32 v[50:51], v[42:43], v[42:43], v[50:51]
	v_pk_fma_f32 v[50:51], v[44:45], v[44:45], v[50:51]
	v_pk_fma_f32 v[50:51], v[46:47], v[46:47], v[50:51]
	v_pk_fma_f32 v[50:51], v[48:49], v[48:49], v[50:51]
	v_add_f32_e32 v52, v50, v51
	s_nop 1
	v_add_f32_dpp v52, v52, v52 quad_perm:[1,0,3,2] row_mask:0xf bank_mask:0xf bound_ctrl:1
	s_nop 1
	v_add_f32_dpp v52, v52, v52 quad_perm:[2,3,0,1] row_mask:0xf bank_mask:0xf bound_ctrl:1
	s_nop 1
	v_add_f32_dpp v52, v52, v52 row_half_mirror row_mask:0xf bank_mask:0xf bound_ctrl:1
	s_nop 1
	v_add_f32_dpp v52, v52, v52 row_mirror row_mask:0xf bank_mask:0xf bound_ctrl:1
	s_nop 1
	v_readlane_b32 s28, v52, 16
	v_readlane_b32 s29, v52, 48
	v_readlane_b32 s24, v52, 0
	v_readlane_b32 s25, v52, 32
	s_nop 1
	v_mov_b32_e32 v52, s28
	v_mov_b32_e32 v53, s29
	v_pk_add_f32 v[52:53], s[24:25], v[52:53]
	s_nop 0
	v_add_f32_e32 v52, v52, v53
	v_fmamk_f32 v52, v52, 0x3a800000, v29
	v_rsq_f32_e32 v54, v52
	s_nop 0
	v_pk_mul_f32 v[56:57], v[54:55], v[34:35] op_sel_hi:[0,1]
	v_pk_mul_f32 v[164:165], v[6:7], v[56:57]
	v_pk_mul_f32 v[56:57], v[54:55], v[36:37] op_sel_hi:[0,1]
	v_pk_mul_f32 v[166:167], v[8:9], v[56:57]
	v_pk_mul_f32 v[56:57], v[54:55], v[38:39] op_sel_hi:[0,1]
	v_pk_mul_f32 v[168:169], v[2:3], v[56:57]
	v_pk_mul_f32 v[56:57], v[54:55], v[40:41] op_sel_hi:[0,1]
	v_pk_mul_f32 v[170:171], v[4:5], v[56:57]
	v_pk_mul_f32 v[56:57], v[54:55], v[42:43] op_sel_hi:[0,1]
	v_pk_mul_f32 v[172:173], v[14:15], v[56:57]
	v_pk_mul_f32 v[56:57], v[54:55], v[44:45] op_sel_hi:[0,1]
	v_pk_mul_f32 v[174:175], v[16:17], v[56:57]
	v_pk_mul_f32 v[56:57], v[54:55], v[46:47] op_sel_hi:[0,1]
	v_pk_mul_f32 v[176:177], v[10:11], v[56:57]
	v_pk_mul_f32 v[56:57], v[54:55], v[48:49] op_sel_hi:[0,1]
	v_pk_mul_f32 v[178:179], v[12:13], v[56:57]
	v_max3_f32 v58, |v164|, 0, |v165|
	v_max3_f32 v58, v58, |v166|, |v167|
	v_max3_f32 v58, v58, |v168|, |v169|
	v_max3_f32 v58, v58, |v170|, |v171|
	v_max3_f32 v58, v58, |v172|, |v173|
	v_max3_f32 v58, v58, |v174|, |v175|
	v_max3_f32 v58, v58, |v176|, |v177|
	v_max3_f32 v58, v58, |v178|, |v179|
	v_cvt_pk_bf16_f32 v62, v164, v165
	v_cvt_pk_bf16_f32 v63, v166, v167
	v_cvt_pk_bf16_f32 v64, v168, v169
	v_cvt_pk_bf16_f32 v65, v170, v171
	v_cvt_pk_bf16_f32 v66, v172, v173
	v_cvt_pk_bf16_f32 v67, v174, v175
	v_cvt_pk_bf16_f32 v68, v176, v177
	v_cvt_pk_bf16_f32 v69, v178, v179
	v_add_u32_e32 v209, 0x18000, v26
	buffer_store_dwordx4 v[62:65], v209, s[12:15], 0 offen sc1
	buffer_store_dwordx4 v[66:69], v209, s[12:15], 0 offen offset:1024 sc1
; __device__ __forceinline__ void xn2_rows(const bf16* __restrict__ hb, const float* __restrict__ g, bf16* __restrict__ outp, unsigned char* __restrict__ xq, float* __restrict__ xs, int gwave, int nwaves, int lane, int rend) {
;     ...
;         mx = wave_max_dpp(mx);
;         const float sc = mx > 0.f ? mx * (1.f / 119.f) : 1.f, inv = 1.f / sc;
;         int sx = 0; unsigned W[4];
; #pragma unroll
;         for (int j = 0; j < 2; ++j) { unsigned wh = 0u, wl = 0u;
; #pragma unroll
;             for (int e = 0; e < 8; ++e) { const int q = (int)rintf(y[j][e] * inv); sx += q; const unsigned tq = (unsigned)(q + 8);
;                 wl |= ((tq & 15u) ^ 8u) << (4 * e); wh |= (((unsigned)((int)tq >> 4)) & 15u) << (4 * e); }
;             W[j] = wh; W[2 + j] = wl; }
;         { const bool o1 = (lane & 1) != 0, o2 = (lane & 2) != 0;
; #pragma unroll
;           for (int p = 0; p < 4; p += 2) { const unsigned t = o1 ? W[p] : W[p + 1]; const unsigned rc = (unsigned)__builtin_amdgcn_update_dpp(0, (int)t, 0xB1, 0xf, 0xf, false); if (o1) W[p] = rc; else W[p + 1] = rc; }
; #pragma unroll
;           for (int p = 0; p < 2; ++p) { const unsigned t = o2 ? W[p] : W[p + 2]; const unsigned rc = (unsigned)__builtin_amdgcn_update_dpp(0, (int)t, 0x4E, 0xf, 0xf, false); if (o2) W[p] = rc; else W[p + 2] = rc; } }
;         { const int m = lane & 3; v4u pw; pw.x = W[0]; pw.y = W[1]; pw.z = W[2]; pw.w = W[3];
;           __builtin_amdgcn_raw_buffer_store_b128(pw, rsQ, (int)((m & 2 ? 8u * (unsigned)MiB : 0u) + (unsigned)row * 512u + (unsigned)(m & 1) * 256u + 16u * (unsigned)(lane >> 2)), 0, 16); }
;         sx = wave_sum_dpp_i(sx);
;         if (lane == 0) { __hip_atomic_store(xs + row, sc, __ATOMIC_RELAXED, __HIP_MEMORY_SCOPE_AGENT); __hip_atomic_store((int*)(xs + T) + row, sx, __ATOMIC_RELAXED, __HIP_MEMORY_SCOPE_AGENT); }
	s_nop 1
	v_max_f32_dpp v58, v58, v58 quad_perm:[1,0,3,2] row_mask:0xf bank_mask:0xf
	s_nop 1
	v_max_f32_dpp v58, v58, v58 quad_perm:[2,3,0,1] row_mask:0xf bank_mask:0xf
	s_nop 1
	v_max_f32_dpp v58, v58, v58 row_half_mirror row_mask:0xf bank_mask:0xf
	s_nop 1
	v_max_f32_dpp v58, v58, v58 row_mirror row_mask:0xf bank_mask:0xf
	s_nop 1
	v_readlane_b32 s28, v58, 32
	v_readlane_b32 s29, v58, 48
	v_readlane_b32 s24, v58, 0
	v_readlane_b32 s25, v58, 16
	s_nop 1
	v_mov_b32_e32 v59, s29
	v_max_f32_e32 v59, s28, v59
	v_mov_b32_e32 v70, s25
	v_max3_f32 v59, s24, v70, v59
	v_mul_f32_e32 v70, 0x3c09ae41, v59
	v_cmp_lt_f32_e32 vcc, 0, v59
	s_nop 1
	v_cndmask_b32_e32 v59, 1.0, v70, vcc
	v_div_scale_f32 v70, s[24:25], v59, v59, 1.0
	v_rcp_f32_e32 v71, v70
	v_div_scale_f32 v72, vcc, 1.0, v59, 1.0
	v_fma_f32 v73, -v70, v71, 1.0
	v_fmac_f32_e32 v71, v73, v71
	v_mul_f32_e32 v73, v72, v71
	v_fma_f32 v74, -v70, v73, v72
	v_fmac_f32_e32 v73, v74, v71
	v_fma_f32 v70, -v70, v73, v72
	v_div_fmas_f32 v70, v70, v71, v73
	v_div_fixup_f32 v60, v70, v59, 1.0
	v_pk_mul_f32 v[56:57], v[60:61], v[164:165] op_sel_hi:[0,1]
	v_pk_add_f32 v[180:181], s[46:47], v[56:57]
	v_pk_mul_f32 v[56:57], v[60:61], v[166:167] op_sel_hi:[0,1]
	v_pk_add_f32 v[182:183], s[46:47], v[56:57]
	v_pk_mul_f32 v[56:57], v[60:61], v[168:169] op_sel_hi:[0,1]
	v_pk_add_f32 v[184:185], s[46:47], v[56:57]
	v_pk_mul_f32 v[56:57], v[60:61], v[170:171] op_sel_hi:[0,1]
	v_pk_add_f32 v[186:187], s[46:47], v[56:57]
	v_pk_mul_f32 v[56:57], v[60:61], v[172:173] op_sel_hi:[0,1]
	v_pk_add_f32 v[188:189], s[46:47], v[56:57]
	v_pk_mul_f32 v[56:57], v[60:61], v[174:175] op_sel_hi:[0,1]
	v_pk_add_f32 v[190:191], s[46:47], v[56:57]
	v_pk_mul_f32 v[56:57], v[60:61], v[176:177] op_sel_hi:[0,1]
	v_pk_add_f32 v[192:193], s[46:47], v[56:57]
	v_pk_mul_f32 v[56:57], v[60:61], v[178:179] op_sel_hi:[0,1]
	v_pk_add_f32 v[194:195], s[46:47], v[56:57]
	v_add3_u32 v208, v180, v181, v182
	v_add3_u32 v208, v208, v183, v184
	v_add3_u32 v208, v208, v185, v186
	v_add3_u32 v208, v208, v187, v188
	v_add3_u32 v208, v208, v189, v190
	v_add3_u32 v208, v208, v191, v192
	v_add3_u32 v208, v208, v193, v194
	v_add_u32_e32 v208, v208, v195
	v_add_u32_e32 v208, 0x4bffff80, v208
	v_perm_b32 v204, v182, v180, s48
	v_perm_b32 v205, v186, v184, s48
	v_perm_b32 v196, v205, v204, s49
	v_perm_b32 v204, v183, v181, s48
	v_perm_b32 v205, v187, v185, s48
	v_perm_b32 v197, v205, v204, s49
	v_lshlrev_b32_e32 v204, 4, v197
	v_lshrrev_b32_e32 v205, 4, v196
	v_bfi_b32 v202, s45, v196, v204
	v_bfi_b32 v200, s45, v205, v197
	v_xor_b32_e32 v202, 0x88888888, v202
	v_perm_b32 v204, v190, v188, s48
	v_perm_b32 v205, v194, v192, s48
	v_perm_b32 v196, v205, v204, s49
	v_perm_b32 v204, v191, v189, s48
	v_perm_b32 v205, v195, v193, s48
	v_perm_b32 v197, v205, v204, s49
	v_lshlrev_b32_e32 v204, 4, v197
	v_lshrrev_b32_e32 v205, 4, v196
	v_bfi_b32 v203, s45, v196, v204
	v_bfi_b32 v201, s45, v205, v197
	v_xor_b32_e32 v203, 0x88888888, v203
	v_cndmask_b32_e64 v204, v200, v201, s[4:5]
	v_cndmask_b32_e64 v205, v202, v203, s[4:5]
	s_nop 1
	v_mov_b32_dpp v206, v204 quad_perm:[1,0,3,2] row_mask:0xf bank_mask:0xf
	v_mov_b32_dpp v207, v205 quad_perm:[1,0,3,2] row_mask:0xf bank_mask:0xf
	s_nop 0
	v_cndmask_b32_e64 v200, v206, v200, s[4:5]
	v_cndmask_b32_e64 v201, v201, v206, s[4:5]
	v_cndmask_b32_e64 v202, v207, v202, s[4:5]
	v_cndmask_b32_e64 v203, v203, v207, s[4:5]
	v_cndmask_b32_e64 v204, v200, v202, s[6:7]
	v_cndmask_b32_e64 v205, v201, v203, s[6:7]
	s_nop 1
	v_mov_b32_dpp v206, v204 quad_perm:[2,3,0,1] row_mask:0xf bank_mask:0xf
	v_mov_b32_dpp v207, v205 quad_perm:[2,3,0,1] row_mask:0xf bank_mask:0xf
	s_nop 0
	v_cndmask_b32_e64 v200, v206, v200, s[6:7]
	v_cndmask_b32_e64 v202, v202, v206, s[6:7]
	v_cndmask_b32_e64 v201, v207, v201, s[6:7]
	v_cndmask_b32_e64 v203, v203, v207, s[6:7]
	v_add_u32_e32 v209, 0x6000, v33
	buffer_store_dwordx4 v[200:203], v209, s[16:19], 0 offen sc1
	s_nop 1
	v_add_u32_dpp v208, v208, v208 quad_perm:[1,0,3,2] row_mask:0xf bank_mask:0xf bound_ctrl:1
	s_nop 1
	v_add_u32_dpp v208, v208, v208 quad_perm:[2,3,0,1] row_mask:0xf bank_mask:0xf bound_ctrl:1
	s_nop 1
	v_add_u32_dpp v208, v208, v208 row_half_mirror row_mask:0xf bank_mask:0xf bound_ctrl:1
	s_nop 1
	v_add_u32_dpp v208, v208, v208 row_mirror row_mask:0xf bank_mask:0xf bound_ctrl:1
	s_nop 1
	v_readlane_b32 s28, v208, 0
	v_readlane_b32 s29, v208, 16
	v_readlane_b32 s30, v208, 32
	v_readlane_b32 s31, v208, 48
	s_nop 1
	s_add_i32 s28, s29, s28
	s_add_i32 s28, s28, s30
	s_add_i32 s30, s28, s31
	s_and_saveexec_b64 s[24:25], s[8:9]
	global_store_dword v30, v59, s[98:99] offset:192 sc1
	v_mov_b32_e32 v70, s30
	global_store_dword v31, v70, s[98:99] offset:192 sc1
	s_mov_b64 exec, s[24:25]
	s_waitcnt vmcnt(35)
; __device__ __forceinline__ void xn2_rows(const bf16* __restrict__ hb, const float* __restrict__ g, bf16* __restrict__ outp, unsigned char* __restrict__ xq, float* __restrict__ xs, int gwave, int nwaves, int lane, int rend) {
;     ...
;         const v4u* xb = (const v4u*)(hb + (size_t)row * D) + lane;
;         float v[2][8]; float ss = 0.f;
; #pragma unroll
;         for (int j = 0; j < 2; ++j) { const v4u w = xb[64 * j]; const unsigned ww[4] = {w.x, w.y, w.z, w.w};
; #pragma unroll
;             for (int e = 0; e < 4; ++e) { v[j][2 * e] = __uint_as_float(ww[e] << 16); v[j][2 * e + 1] = __uint_as_float(ww[e] & 0xffff0000u); ss += v[j][2 * e] * v[j][2 * e] + v[j][2 * e + 1] * v[j][2 * e + 1]; } }
;         ss = wave_sum(ss);
;         const float r = rsqrtf(ss * (1.f / D) + EPS);
;         float y[2][8]; float mx = 0.f;
; #pragma unroll
;         for (int j = 0; j < 2; ++j) { const float4 g0 = ((const float4*)g)[2 * lane + 128 * j], g1 = ((const float4*)g)[2 * lane + 128 * j + 1]; const float gg[8] = {g0.x, g0.y, g0.z, g0.w, g1.x, g1.y, g1.z, g1.w};
; #pragma unroll
;             for (int e = 0; e < 8; ++e) { y[j][e] = v[j][e] * r * gg[e]; mx = fmaxf(mx, fabsf(y[j][e])); }
;             v4u ow; ow.x = pk2(y[j][0], y[j][1]); ow.y = pk2(y[j][2], y[j][3]); ow.z = pk2(y[j][4], y[j][5]); ow.w = pk2(y[j][6], y[j][7]);
;             __builtin_amdgcn_raw_buffer_store_b128(ow, rsO, (int)(((unsigned)row * D + 8u * (unsigned)lane + 512u * j) * 2u), 0, 16); }
;         mx = wave_max_dpp(mx);
;         const float sc = mx > 0.f ? mx * (1.f / 119.f) : 1.f, inv = 1.f / sc;
	v_lshlrev_b32_e32 v34, 16, v140
	v_and_b32_e32 v35, 0xffff0000, v140
	v_lshlrev_b32_e32 v36, 16, v141
	v_and_b32_e32 v37, 0xffff0000, v141
	v_lshlrev_b32_e32 v38, 16, v142
	v_and_b32_e32 v39, 0xffff0000, v142
	v_lshlrev_b32_e32 v40, 16, v143
	v_and_b32_e32 v41, 0xffff0000, v143
	v_lshlrev_b32_e32 v42, 16, v144
	v_and_b32_e32 v43, 0xffff0000, v144
	v_lshlrev_b32_e32 v44, 16, v145
	v_and_b32_e32 v45, 0xffff0000, v145
	v_lshlrev_b32_e32 v46, 16, v146
	v_and_b32_e32 v47, 0xffff0000, v146
	v_lshlrev_b32_e32 v48, 16, v147
	v_and_b32_e32 v49, 0xffff0000, v147
	v_pk_mul_f32 v[50:51], v[34:35], v[34:35]
	v_pk_fma_f32 v[50:51], v[36:37], v[36:37], v[50:51]
	v_pk_fma_f32 v[50:51], v[38:39], v[38:39], v[50:51]
	v_pk_fma_f32 v[50:51], v[40:41], v[40:41], v[50:51]
	v_pk_fma_f32 v[50:51], v[42:43], v[42:43], v[50:51]
	v_pk_fma_f32 v[50:51], v[44:45], v[44:45], v[50:51]
	v_pk_fma_f32 v[50:51], v[46:47], v[46:47], v[50:51]
	v_pk_fma_f32 v[50:51], v[48:49], v[48:49], v[50:51]
	v_add_f32_e32 v52, v50, v51
	s_nop 1
	v_add_f32_dpp v52, v52, v52 quad_perm:[1,0,3,2] row_mask:0xf bank_mask:0xf bound_ctrl:1
	s_nop 1
	v_add_f32_dpp v52, v52, v52 quad_perm:[2,3,0,1] row_mask:0xf bank_mask:0xf bound_ctrl:1
	s_nop 1
	v_add_f32_dpp v52, v52, v52 row_half_mirror row_mask:0xf bank_mask:0xf bound_ctrl:1
	s_nop 1
	v_add_f32_dpp v52, v52, v52 row_mirror row_mask:0xf bank_mask:0xf bound_ctrl:1
	s_nop 1
	v_readlane_b32 s28, v52, 16
	v_readlane_b32 s29, v52, 48
	v_readlane_b32 s24, v52, 0
	v_readlane_b32 s25, v52, 32
	s_nop 1
	v_mov_b32_e32 v52, s28
	v_mov_b32_e32 v53, s29
	v_pk_add_f32 v[52:53], s[24:25], v[52:53]
	s_nop 0
	v_add_f32_e32 v52, v52, v53
	v_fmamk_f32 v52, v52, 0x3a800000, v29
	v_rsq_f32_e32 v54, v52
	s_nop 0
	v_pk_mul_f32 v[56:57], v[54:55], v[34:35] op_sel_hi:[0,1]
	v_pk_mul_f32 v[164:165], v[6:7], v[56:57]
	v_pk_mul_f32 v[56:57], v[54:55], v[36:37] op_sel_hi:[0,1]
	v_pk_mul_f32 v[166:167], v[8:9], v[56:57]
	v_pk_mul_f32 v[56:57], v[54:55], v[38:39] op_sel_hi:[0,1]
	v_pk_mul_f32 v[168:169], v[2:3], v[56:57]
	v_pk_mul_f32 v[56:57], v[54:55], v[40:41] op_sel_hi:[0,1]
	v_pk_mul_f32 v[170:171], v[4:5], v[56:57]
	v_pk_mul_f32 v[56:57], v[54:55], v[42:43] op_sel_hi:[0,1]
	v_pk_mul_f32 v[172:173], v[14:15], v[56:57]
	v_pk_mul_f32 v[56:57], v[54:55], v[44:45] op_sel_hi:[0,1]
	v_pk_mul_f32 v[174:175], v[16:17], v[56:57]
	v_pk_mul_f32 v[56:57], v[54:55], v[46:47] op_sel_hi:[0,1]
	v_pk_mul_f32 v[176:177], v[10:11], v[56:57]
	v_pk_mul_f32 v[56:57], v[54:55], v[48:49] op_sel_hi:[0,1]
	v_pk_mul_f32 v[178:179], v[12:13], v[56:57]
	v_max3_f32 v58, |v164|, 0, |v165|
	v_max3_f32 v58, v58, |v166|, |v167|
	v_max3_f32 v58, v58, |v168|, |v169|
	v_max3_f32 v58, v58, |v170|, |v171|
	v_max3_f32 v58, v58, |v172|, |v173|
	v_max3_f32 v58, v58, |v174|, |v175|
	v_max3_f32 v58, v58, |v176|, |v177|
	v_max3_f32 v58, v58, |v178|, |v179|
	v_cvt_pk_bf16_f32 v62, v164, v165
	v_cvt_pk_bf16_f32 v63, v166, v167
	v_cvt_pk_bf16_f32 v64, v168, v169
	v_cvt_pk_bf16_f32 v65, v170, v171
	v_cvt_pk_bf16_f32 v66, v172, v173
	v_cvt_pk_bf16_f32 v67, v174, v175
	v_cvt_pk_bf16_f32 v68, v176, v177
	v_cvt_pk_bf16_f32 v69, v178, v179
	v_add_u32_e32 v209, 0x1c000, v26
	buffer_store_dwordx4 v[62:65], v209, s[12:15], 0 offen sc1
	buffer_store_dwordx4 v[66:69], v209, s[12:15], 0 offen offset:1024 sc1
	s_nop 1
	v_max_f32_dpp v58, v58, v58 quad_perm:[1,0,3,2] row_mask:0xf bank_mask:0xf
	s_nop 1
	v_max_f32_dpp v58, v58, v58 quad_perm:[2,3,0,1] row_mask:0xf bank_mask:0xf
	s_nop 1
	v_max_f32_dpp v58, v58, v58 row_half_mirror row_mask:0xf bank_mask:0xf
	s_nop 1
	v_max_f32_dpp v58, v58, v58 row_mirror row_mask:0xf bank_mask:0xf
	s_nop 1
	v_readlane_b32 s28, v58, 32
	v_readlane_b32 s29, v58, 48
	v_readlane_b32 s24, v58, 0
	v_readlane_b32 s25, v58, 16
	s_nop 1
	v_mov_b32_e32 v59, s29
	v_max_f32_e32 v59, s28, v59
	v_mov_b32_e32 v70, s25
	v_max3_f32 v59, s24, v70, v59
	v_mul_f32_e32 v70, 0x3c09ae41, v59
	v_cmp_lt_f32_e32 vcc, 0, v59
	s_nop 1
	v_cndmask_b32_e32 v59, 1.0, v70, vcc
	v_div_scale_f32 v70, s[24:25], v59, v59, 1.0
; __device__ __forceinline__ void xn2_rows(const bf16* __restrict__ hb, const float* __restrict__ g, bf16* __restrict__ outp, unsigned char* __restrict__ xq, float* __restrict__ xs, int gwave, int nwaves, int lane, int rend) {
;     ...
;         const float sc = mx > 0.f ? mx * (1.f / 119.f) : 1.f, inv = 1.f / sc;
;         int sx = 0; unsigned W[4];
; #pragma unroll
;         for (int j = 0; j < 2; ++j) { unsigned wh = 0u, wl = 0u;
; #pragma unroll
;             for (int e = 0; e < 8; ++e) { const int q = (int)rintf(y[j][e] * inv); sx += q; const unsigned tq = (unsigned)(q + 8);
;                 wl |= ((tq & 15u) ^ 8u) << (4 * e); wh |= (((unsigned)((int)tq >> 4)) & 15u) << (4 * e); }
;             W[j] = wh; W[2 + j] = wl; }
;         { const bool o1 = (lane & 1) != 0, o2 = (lane & 2) != 0;
; #pragma unroll
;           for (int p = 0; p < 4; p += 2) { const unsigned t = o1 ? W[p] : W[p + 1]; const unsigned rc = (unsigned)__builtin_amdgcn_update_dpp(0, (int)t, 0xB1, 0xf, 0xf, false); if (o1) W[p] = rc; else W[p + 1] = rc; }
; #pragma unroll
;           for (int p = 0; p < 2; ++p) { const unsigned t = o2 ? W[p] : W[p + 2]; const unsigned rc = (unsigned)__builtin_amdgcn_update_dpp(0, (int)t, 0x4E, 0xf, 0xf, false); if (o2) W[p] = rc; else W[p + 2] = rc; } }
;         { const int m = lane & 3; v4u pw; pw.x = W[0]; pw.y = W[1]; pw.z = W[2]; pw.w = W[3];
;           __builtin_amdgcn_raw_buffer_store_b128(pw, rsQ, (int)((m & 2 ? 8u * (unsigned)MiB : 0u) + (unsigned)row * 512u + (unsigned)(m & 1) * 256u + 16u * (unsigned)(lane >> 2)), 0, 16); }
;         sx = wave_sum_dpp_i(sx);
;         if (lane == 0) { __hip_atomic_store(xs + row, sc, __ATOMIC_RELAXED, __HIP_MEMORY_SCOPE_AGENT); __hip_atomic_store((int*)(xs + T) + row, sx, __ATOMIC_RELAXED, __HIP_MEMORY_SCOPE_AGENT); }
	v_rcp_f32_e32 v71, v70
	v_div_scale_f32 v72, vcc, 1.0, v59, 1.0
	v_fma_f32 v73, -v70, v71, 1.0
	v_fmac_f32_e32 v71, v73, v71
	v_mul_f32_e32 v73, v72, v71
	v_fma_f32 v74, -v70, v73, v72
	v_fmac_f32_e32 v73, v74, v71
	v_fma_f32 v70, -v70, v73, v72
	v_div_fmas_f32 v70, v70, v71, v73
	v_div_fixup_f32 v60, v70, v59, 1.0
	v_pk_mul_f32 v[56:57], v[60:61], v[164:165] op_sel_hi:[0,1]
	v_pk_add_f32 v[180:181], s[46:47], v[56:57]
	v_pk_mul_f32 v[56:57], v[60:61], v[166:167] op_sel_hi:[0,1]
	v_pk_add_f32 v[182:183], s[46:47], v[56:57]
	v_pk_mul_f32 v[56:57], v[60:61], v[168:169] op_sel_hi:[0,1]
	v_pk_add_f32 v[184:185], s[46:47], v[56:57]
	v_pk_mul_f32 v[56:57], v[60:61], v[170:171] op_sel_hi:[0,1]
	v_pk_add_f32 v[186:187], s[46:47], v[56:57]
	v_pk_mul_f32 v[56:57], v[60:61], v[172:173] op_sel_hi:[0,1]
	v_pk_add_f32 v[188:189], s[46:47], v[56:57]
	v_pk_mul_f32 v[56:57], v[60:61], v[174:175] op_sel_hi:[0,1]
	v_pk_add_f32 v[190:191], s[46:47], v[56:57]
	v_pk_mul_f32 v[56:57], v[60:61], v[176:177] op_sel_hi:[0,1]
	v_pk_add_f32 v[192:193], s[46:47], v[56:57]
	v_pk_mul_f32 v[56:57], v[60:61], v[178:179] op_sel_hi:[0,1]
	v_pk_add_f32 v[194:195], s[46:47], v[56:57]
	v_add3_u32 v208, v180, v181, v182
	v_add3_u32 v208, v208, v183, v184
	v_add3_u32 v208, v208, v185, v186
	v_add3_u32 v208, v208, v187, v188
	v_add3_u32 v208, v208, v189, v190
	v_add3_u32 v208, v208, v191, v192
	v_add3_u32 v208, v208, v193, v194
	v_add_u32_e32 v208, v208, v195
	v_add_u32_e32 v208, 0x4bffff80, v208
	v_perm_b32 v204, v182, v180, s48
	v_perm_b32 v205, v186, v184, s48
	v_perm_b32 v196, v205, v204, s49
	v_perm_b32 v204, v183, v181, s48
	v_perm_b32 v205, v187, v185, s48
	v_perm_b32 v197, v205, v204, s49
	v_lshlrev_b32_e32 v204, 4, v197
	v_lshrrev_b32_e32 v205, 4, v196
	v_bfi_b32 v202, s45, v196, v204
	v_bfi_b32 v200, s45, v205, v197
	v_xor_b32_e32 v202, 0x88888888, v202
	v_perm_b32 v204, v190, v188, s48
	v_perm_b32 v205, v194, v192, s48
	v_perm_b32 v196, v205, v204, s49
	v_perm_b32 v204, v191, v189, s48
	v_perm_b32 v205, v195, v193, s48
	v_perm_b32 v197, v205, v204, s49
	v_lshlrev_b32_e32 v204, 4, v197
	v_lshrrev_b32_e32 v205, 4, v196
	v_bfi_b32 v203, s45, v196, v204
	v_bfi_b32 v201, s45, v205, v197
	v_xor_b32_e32 v203, 0x88888888, v203
	v_cndmask_b32_e64 v204, v200, v201, s[4:5]
	v_cndmask_b32_e64 v205, v202, v203, s[4:5]
	s_nop 1
	v_mov_b32_dpp v206, v204 quad_perm:[1,0,3,2] row_mask:0xf bank_mask:0xf
	v_mov_b32_dpp v207, v205 quad_perm:[1,0,3,2] row_mask:0xf bank_mask:0xf
	s_nop 0
	v_cndmask_b32_e64 v200, v206, v200, s[4:5]
	v_cndmask_b32_e64 v201, v201, v206, s[4:5]
	v_cndmask_b32_e64 v202, v207, v202, s[4:5]
	v_cndmask_b32_e64 v203, v203, v207, s[4:5]
	v_cndmask_b32_e64 v204, v200, v202, s[6:7]
	v_cndmask_b32_e64 v205, v201, v203, s[6:7]
	s_nop 1
	v_mov_b32_dpp v206, v204 quad_perm:[2,3,0,1] row_mask:0xf bank_mask:0xf
	v_mov_b32_dpp v207, v205 quad_perm:[2,3,0,1] row_mask:0xf bank_mask:0xf
	s_nop 0
	v_cndmask_b32_e64 v200, v206, v200, s[6:7]
	v_cndmask_b32_e64 v202, v202, v206, s[6:7]
	v_cndmask_b32_e64 v201, v207, v201, s[6:7]
	v_cndmask_b32_e64 v203, v203, v207, s[6:7]
	v_add_u32_e32 v209, 0x7000, v33
	buffer_store_dwordx4 v[200:203], v209, s[16:19], 0 offen sc1
	s_nop 1
	v_add_u32_dpp v208, v208, v208 quad_perm:[1,0,3,2] row_mask:0xf bank_mask:0xf bound_ctrl:1
	s_nop 1
	v_add_u32_dpp v208, v208, v208 quad_perm:[2,3,0,1] row_mask:0xf bank_mask:0xf bound_ctrl:1
	s_nop 1
	v_add_u32_dpp v208, v208, v208 row_half_mirror row_mask:0xf bank_mask:0xf bound_ctrl:1
	s_nop 1
	v_add_u32_dpp v208, v208, v208 row_mirror row_mask:0xf bank_mask:0xf bound_ctrl:1
	s_nop 1
	v_readlane_b32 s28, v208, 0
	v_readlane_b32 s29, v208, 16
	v_readlane_b32 s30, v208, 32
	v_readlane_b32 s31, v208, 48
	s_nop 1
	s_add_i32 s28, s29, s28
	s_add_i32 s28, s28, s30
	s_add_i32 s30, s28, s31
	s_and_saveexec_b64 s[24:25], s[8:9]
	global_store_dword v30, v59, s[98:99] offset:224 sc1
	v_mov_b32_e32 v70, s30
	global_store_dword v31, v70, s[98:99] offset:224 sc1
	s_mov_b64 exec, s[24:25]
